# 64-byte alignment of the K-loop heads and the attention loop head
# baseline (speedup 1.0000x reference)
; template <class Epi, bool ALIGN_EPI>
; __device__ __forceinline__ void gemm_phase(LAS unsigned char* lds, const Gemm g, const StaticOrder& S, const Epi& E) {
;     ...
; #pragma unroll
;     for (int a = 0; a < 2; ++a)
; #pragma unroll
;         for (int b = 0; b < 2; ++b)
; #pragma unroll
;             for (int m = 0; m < 4; ++m)
; #pragma unroll
;                 for (int n = 0; n < 2; ++n) acc[a][b][m][n] = (f32x4){0.f, 0.f, 0.f, 0.f};
;     ...
;         const bool has_next = S.next(ui + 1, nxt);
;         const char* nA = has_next ? (const char*)g.A + (size_t)nxt.pb * g.sA * 2 + (size_t)nxt.pm * tsA : cA; const char* nB = has_next ? (const char*)g.Bt + (size_t)nxt.pb * g.sB * 2 + (size_t)nxt.pn * tsB : cB;
;         for (int t = 0; t < nt; t += 2) {
.LBB0_155:
	s_ashr_i32 s17, s16, 31
	s_lshl_b64 s[20:21], s[16:17], 19
	s_add_u32 s20, s72, s20
	s_addc_u32 s21, s73, s21
	s_and_b64 s[22:23], s[2:3], exec
	s_cselect_b32 s17, s21, s27
	s_cselect_b32 s50, s20, s26
	s_ashr_i32 s19, s18, 31
	s_lshl_b64 s[22:23], s[18:19], 19
	s_add_u32 s22, s4, s22
	s_addc_u32 s23, s5, s23
	s_and_b64 s[30:31], s[2:3], exec
	s_cselect_b32 s19, s23, s29
	s_cselect_b32 s51, s22, s28
	s_add_u32 s26, s26, 0x40080
	s_addc_u32 s27, s27, 0
	s_add_u32 s52, s28, 0x100
	v_mov_b32_e32 v2, 0
	s_addc_u32 s53, s29, 0
	s_mov_b32 s54, -2
	v_mov_b32_e32 v3, v2
	v_mov_b32_e32 v4, v2
	v_mov_b32_e32 v5, v2
	v_mov_b32_e32 v6, v2
	v_mov_b32_e32 v7, v2
	v_mov_b32_e32 v8, v2
	v_mov_b32_e32 v9, v2
	v_mov_b32_e32 v18, v2
	v_mov_b32_e32 v19, v2
	v_mov_b32_e32 v20, v2
	v_mov_b32_e32 v21, v2
	v_mov_b32_e32 v22, v2
	v_mov_b32_e32 v23, v2
	v_mov_b32_e32 v24, v2
	v_mov_b32_e32 v25, v2
	v_mov_b32_e32 v34, v2
	v_mov_b32_e32 v35, v2
	v_mov_b32_e32 v36, v2
	v_mov_b32_e32 v37, v2
	v_mov_b32_e32 v38, v2
	v_mov_b32_e32 v39, v2
	v_mov_b32_e32 v40, v2
	v_mov_b32_e32 v41, v2
	v_mov_b32_e32 v50, v2
	v_mov_b32_e32 v51, v2
	v_mov_b32_e32 v52, v2
	v_mov_b32_e32 v53, v2
	v_mov_b32_e32 v54, v2
	v_mov_b32_e32 v55, v2
	v_mov_b32_e32 v56, v2
	v_mov_b32_e32 v57, v2
	v_mov_b32_e32 v10, v2
	v_mov_b32_e32 v11, v2
	v_mov_b32_e32 v12, v2
	v_mov_b32_e32 v13, v2
	v_mov_b32_e32 v14, v2
	v_mov_b32_e32 v15, v2
	v_mov_b32_e32 v16, v2
	v_mov_b32_e32 v17, v2
	v_mov_b32_e32 v26, v2
	v_mov_b32_e32 v27, v2
	v_mov_b32_e32 v28, v2
	v_mov_b32_e32 v29, v2
	v_mov_b32_e32 v30, v2
	v_mov_b32_e32 v31, v2
	v_mov_b32_e32 v32, v2
	v_mov_b32_e32 v33, v2
	v_mov_b32_e32 v42, v2
	v_mov_b32_e32 v43, v2
	v_mov_b32_e32 v44, v2
	v_mov_b32_e32 v45, v2
	v_mov_b32_e32 v46, v2
	v_mov_b32_e32 v47, v2
	v_mov_b32_e32 v48, v2
	v_mov_b32_e32 v49, v2
	v_mov_b32_e32 v58, v2
	v_mov_b32_e32 v59, v2
	v_mov_b32_e32 v60, v2
	v_mov_b32_e32 v61, v2
	v_mov_b32_e32 v62, v2
	v_mov_b32_e32 v63, v2
	v_mov_b32_e32 v64, v2
	v_mov_b32_e32 v65, v2
	v_mov_b32_e32 v66, v2
	v_mov_b32_e32 v67, v2
	v_mov_b32_e32 v68, v2
	v_mov_b32_e32 v69, v2
	v_mov_b32_e32 v70, v2
	v_mov_b32_e32 v71, v2
	v_mov_b32_e32 v72, v2
	v_mov_b32_e32 v73, v2
	v_mov_b32_e32 v82, v2
	v_mov_b32_e32 v83, v2
	v_mov_b32_e32 v84, v2
	v_mov_b32_e32 v85, v2
	v_mov_b32_e32 v86, v2
	v_mov_b32_e32 v87, v2
	v_mov_b32_e32 v88, v2
	v_mov_b32_e32 v89, v2
	v_mov_b32_e32 v98, v2
	v_mov_b32_e32 v99, v2
	v_mov_b32_e32 v100, v2
	v_mov_b32_e32 v101, v2
	v_mov_b32_e32 v110, v2
	v_mov_b32_e32 v111, v2
	v_mov_b32_e32 v112, v2
	v_mov_b32_e32 v113, v2
	v_mov_b32_e32 v122, v2
	v_mov_b32_e32 v123, v2
	v_mov_b32_e32 v124, v2
	v_mov_b32_e32 v125, v2
	v_mov_b32_e32 v126, v2
	v_mov_b32_e32 v127, v2
	v_mov_b32_e32 v128, v2
	v_mov_b32_e32 v129, v2
	v_mov_b32_e32 v74, v2
	v_mov_b32_e32 v75, v2
	v_mov_b32_e32 v76, v2
	v_mov_b32_e32 v77, v2
	v_mov_b32_e32 v78, v2
	v_mov_b32_e32 v79, v2
	v_mov_b32_e32 v80, v2
	v_mov_b32_e32 v81, v2
	v_mov_b32_e32 v90, v2
	v_mov_b32_e32 v91, v2
	v_mov_b32_e32 v92, v2
	v_mov_b32_e32 v93, v2
	v_mov_b32_e32 v94, v2
	v_mov_b32_e32 v95, v2
	v_mov_b32_e32 v96, v2
	v_mov_b32_e32 v97, v2
	v_mov_b32_e32 v102, v2
	v_mov_b32_e32 v103, v2
	v_mov_b32_e32 v104, v2
	v_mov_b32_e32 v105, v2
	v_mov_b32_e32 v106, v2
	v_mov_b32_e32 v107, v2
	v_mov_b32_e32 v108, v2
	v_mov_b32_e32 v109, v2
	v_mov_b32_e32 v114, v2
	v_mov_b32_e32 v115, v2
	v_mov_b32_e32 v116, v2
	v_mov_b32_e32 v117, v2
	v_mov_b32_e32 v118, v2
	v_mov_b32_e32 v119, v2
	v_mov_b32_e32 v120, v2
	v_mov_b32_e32 v121, v2
	.p2align 6

; template <class Epi, bool ALIGN_EPI>
; __device__ __forceinline__ void gemm_phase(LAS unsigned char* lds, const Gemm g, const StaticOrder& S, const Epi& E) {
;     ...
; #pragma unroll
;     for (int a = 0; a < 2; ++a)
; #pragma unroll
;         for (int b = 0; b < 2; ++b)
; #pragma unroll
;             for (int m = 0; m < 4; ++m)
; #pragma unroll
;                 for (int n = 0; n < 2; ++n) acc[a][b][m][n] = (f32x4){0.f, 0.f, 0.f, 0.f};
;     ...
;         const bool has_next = S.next(ui + 1, nxt);
;         const char* nA = has_next ? (const char*)g.A + (size_t)nxt.pb * g.sA * 2 + (size_t)nxt.pm * tsA : cA; const char* nB = has_next ? (const char*)g.Bt + (size_t)nxt.pb * g.sB * 2 + (size_t)nxt.pn * tsB : cB;
;         for (int t = 0; t < nt; t += 2) {
.LBB0_329:
	s_add_u32 s12, s12, 0xc000
	s_addc_u32 s13, s13, 0
	s_add_u32 s46, s14, 0x100
	v_mov_b32_e32 v2, 0
	s_addc_u32 s47, s15, 0
	s_mov_b32 s48, -2
	s_waitcnt lgkmcnt(0)
	v_mov_b32_e32 v3, v2
	v_mov_b32_e32 v4, v2
	v_mov_b32_e32 v5, v2
	v_mov_b32_e32 v6, v2
	v_mov_b32_e32 v7, v2
	v_mov_b32_e32 v8, v2
	v_mov_b32_e32 v9, v2
	v_mov_b32_e32 v18, v2
	v_mov_b32_e32 v19, v2
	v_mov_b32_e32 v20, v2
	v_mov_b32_e32 v21, v2
	v_mov_b32_e32 v22, v2
	v_mov_b32_e32 v23, v2
	v_mov_b32_e32 v24, v2
	v_mov_b32_e32 v25, v2
	v_mov_b32_e32 v34, v2
	v_mov_b32_e32 v35, v2
	v_mov_b32_e32 v36, v2
	v_mov_b32_e32 v37, v2
	v_mov_b32_e32 v38, v2
	v_mov_b32_e32 v39, v2
	v_mov_b32_e32 v40, v2
	v_mov_b32_e32 v41, v2
	v_mov_b32_e32 v50, v2
	v_mov_b32_e32 v51, v2
	v_mov_b32_e32 v52, v2
	v_mov_b32_e32 v53, v2
	v_mov_b32_e32 v54, v2
	v_mov_b32_e32 v55, v2
	v_mov_b32_e32 v56, v2
	v_mov_b32_e32 v57, v2
	v_mov_b32_e32 v10, v2
	v_mov_b32_e32 v11, v2
	v_mov_b32_e32 v12, v2
	v_mov_b32_e32 v13, v2
	v_mov_b32_e32 v14, v2
	v_mov_b32_e32 v15, v2
	v_mov_b32_e32 v16, v2
	v_mov_b32_e32 v17, v2
	v_mov_b32_e32 v26, v2
	v_mov_b32_e32 v27, v2
	v_mov_b32_e32 v28, v2
	v_mov_b32_e32 v29, v2
	v_mov_b32_e32 v30, v2
	v_mov_b32_e32 v31, v2
	v_mov_b32_e32 v32, v2
	v_mov_b32_e32 v33, v2
	v_mov_b32_e32 v42, v2
	v_mov_b32_e32 v43, v2
	v_mov_b32_e32 v44, v2
	v_mov_b32_e32 v45, v2
	v_mov_b32_e32 v46, v2
	v_mov_b32_e32 v47, v2
	v_mov_b32_e32 v48, v2
	v_mov_b32_e32 v49, v2
	v_mov_b32_e32 v58, v2
	v_mov_b32_e32 v59, v2
	v_mov_b32_e32 v60, v2
	v_mov_b32_e32 v61, v2
	v_mov_b32_e32 v62, v2
	v_mov_b32_e32 v63, v2
	v_mov_b32_e32 v64, v2
	v_mov_b32_e32 v65, v2
	v_mov_b32_e32 v66, v2
	v_mov_b32_e32 v67, v2
	v_mov_b32_e32 v68, v2
	v_mov_b32_e32 v69, v2
	v_mov_b32_e32 v70, v2
	v_mov_b32_e32 v71, v2
	v_mov_b32_e32 v72, v2
	v_mov_b32_e32 v73, v2
	v_mov_b32_e32 v82, v2
	v_mov_b32_e32 v83, v2
	v_mov_b32_e32 v84, v2
	v_mov_b32_e32 v85, v2
	v_mov_b32_e32 v86, v2
	v_mov_b32_e32 v87, v2
	v_mov_b32_e32 v88, v2
	v_mov_b32_e32 v89, v2
	v_mov_b32_e32 v98, v2
	v_mov_b32_e32 v99, v2
	v_mov_b32_e32 v100, v2
	v_mov_b32_e32 v101, v2
	v_mov_b32_e32 v102, v2
	v_mov_b32_e32 v103, v2
	v_mov_b32_e32 v104, v2
	v_mov_b32_e32 v105, v2
	v_mov_b32_e32 v114, v2
	v_mov_b32_e32 v115, v2
	v_mov_b32_e32 v116, v2
	v_mov_b32_e32 v117, v2
	v_mov_b32_e32 v122, v2
	v_mov_b32_e32 v123, v2
	v_mov_b32_e32 v124, v2
	v_mov_b32_e32 v125, v2
	v_mov_b32_e32 v74, v2
	v_mov_b32_e32 v75, v2
	v_mov_b32_e32 v76, v2
	v_mov_b32_e32 v77, v2
	v_mov_b32_e32 v78, v2
	v_mov_b32_e32 v79, v2
	v_mov_b32_e32 v80, v2
	v_mov_b32_e32 v81, v2
	v_mov_b32_e32 v90, v2
	v_mov_b32_e32 v91, v2
	v_mov_b32_e32 v92, v2
	v_mov_b32_e32 v93, v2
	v_mov_b32_e32 v94, v2
	v_mov_b32_e32 v95, v2
	v_mov_b32_e32 v96, v2
	v_mov_b32_e32 v97, v2
	v_mov_b32_e32 v106, v2
	v_mov_b32_e32 v107, v2
	v_mov_b32_e32 v108, v2
	v_mov_b32_e32 v109, v2
	v_mov_b32_e32 v110, v2
	v_mov_b32_e32 v111, v2
	v_mov_b32_e32 v112, v2
	v_mov_b32_e32 v113, v2
	v_mov_b32_e32 v130, v2
	v_mov_b32_e32 v131, v2
	v_mov_b32_e32 v132, v2
	v_mov_b32_e32 v133, v2
	v_mov_b32_e32 v134, v2
	v_mov_b32_e32 v135, v2
	v_mov_b32_e32 v136, v2
	v_mov_b32_e32 v137, v2
	.p2align 6

; template <class Epi, bool ALIGN_EPI>
; __device__ __forceinline__ void gemm_phase(LAS unsigned char* lds, const Gemm g, const StaticOrder& S, const Epi& E) {
;     ...
; #pragma unroll
;     for (int a = 0; a < 2; ++a)
; #pragma unroll
;         for (int b = 0; b < 2; ++b)
; #pragma unroll
;             for (int m = 0; m < 4; ++m)
; #pragma unroll
;                 for (int n = 0; n < 2; ++n) acc[a][b][m][n] = (f32x4){0.f, 0.f, 0.f, 0.f};
;     ...
;         const bool has_next = S.next(ui + 1, nxt);
;         const char* nA = has_next ? (const char*)g.A + (size_t)nxt.pb * g.sA * 2 + (size_t)nxt.pm * tsA : cA; const char* nB = has_next ? (const char*)g.Bt + (size_t)nxt.pb * g.sB * 2 + (size_t)nxt.pn * tsB : cB;
;         for (int t = 0; t < nt; t += 2) {
.LBB0_418:
	s_ashr_i32 s75, s74, 31
	s_lshl_b64 s[14:15], s[74:75], 19
	s_add_u32 s82, s72, s14
	s_addc_u32 s83, s73, s15
	s_and_b64 s[14:15], s[4:5], exec
	s_cselect_b32 s7, s83, s9
	s_cselect_b32 s33, s82, s8
	s_ashr_i32 s81, s80, 31
	s_lshl_b64 s[14:15], s[80:81], 19
	s_add_u32 s36, s0, s14
	s_addc_u32 s37, s1, s15
	s_and_b64 s[14:15], s[4:5], exec
	s_cselect_b32 s39, s37, s13
	s_cselect_b32 s40, s36, s12
	s_add_u32 s8, s8, 0x40080
	s_addc_u32 s9, s9, 0
	s_add_u32 s41, s12, 0x100
	v_mov_b32_e32 v6, 0
	s_addc_u32 s42, s13, 0
	s_mov_b32 s43, -2
	v_mov_b32_e32 v7, v6
	v_mov_b32_e32 v8, v6
	v_mov_b32_e32 v9, v6
	v_mov_b32_e32 v2, v6
	v_mov_b32_e32 v3, v6
	v_mov_b32_e32 v4, v6
	v_mov_b32_e32 v5, v6
	v_mov_b32_e32 v22, v6
	v_mov_b32_e32 v23, v6
	v_mov_b32_e32 v24, v6
	v_mov_b32_e32 v25, v6
	v_mov_b32_e32 v18, v6
	v_mov_b32_e32 v19, v6
	v_mov_b32_e32 v20, v6
	v_mov_b32_e32 v21, v6
	v_mov_b32_e32 v38, v6
	v_mov_b32_e32 v39, v6
	v_mov_b32_e32 v40, v6
	v_mov_b32_e32 v41, v6
	v_mov_b32_e32 v34, v6
	v_mov_b32_e32 v35, v6
	v_mov_b32_e32 v36, v6
	v_mov_b32_e32 v37, v6
	v_mov_b32_e32 v54, v6
	v_mov_b32_e32 v55, v6
	v_mov_b32_e32 v56, v6
	v_mov_b32_e32 v57, v6
	v_mov_b32_e32 v50, v6
	v_mov_b32_e32 v51, v6
	v_mov_b32_e32 v52, v6
	v_mov_b32_e32 v53, v6
	v_mov_b32_e32 v14, v6
	v_mov_b32_e32 v15, v6
	v_mov_b32_e32 v16, v6
	v_mov_b32_e32 v17, v6
	v_mov_b32_e32 v10, v6
	v_mov_b32_e32 v11, v6
	v_mov_b32_e32 v12, v6
	v_mov_b32_e32 v13, v6
	v_mov_b32_e32 v30, v6
	v_mov_b32_e32 v31, v6
	v_mov_b32_e32 v32, v6
	v_mov_b32_e32 v33, v6
	v_mov_b32_e32 v26, v6
	v_mov_b32_e32 v27, v6
	v_mov_b32_e32 v28, v6
	v_mov_b32_e32 v29, v6
	v_mov_b32_e32 v46, v6
	v_mov_b32_e32 v47, v6
	v_mov_b32_e32 v48, v6
	v_mov_b32_e32 v49, v6
	v_mov_b32_e32 v42, v6
	v_mov_b32_e32 v43, v6
	v_mov_b32_e32 v44, v6
	v_mov_b32_e32 v45, v6
	v_mov_b32_e32 v62, v6
	v_mov_b32_e32 v63, v6
	v_mov_b32_e32 v64, v6
	v_mov_b32_e32 v65, v6
	v_mov_b32_e32 v58, v6
	v_mov_b32_e32 v59, v6
	v_mov_b32_e32 v60, v6
	v_mov_b32_e32 v61, v6
	v_mov_b32_e32 v70, v6
	v_mov_b32_e32 v71, v6
	v_mov_b32_e32 v72, v6
	v_mov_b32_e32 v73, v6
	v_mov_b32_e32 v66, v6
	v_mov_b32_e32 v67, v6
	v_mov_b32_e32 v68, v6
	v_mov_b32_e32 v69, v6
	v_mov_b32_e32 v86, v6
	v_mov_b32_e32 v87, v6
	v_mov_b32_e32 v88, v6
	v_mov_b32_e32 v89, v6
	v_mov_b32_e32 v82, v6
	v_mov_b32_e32 v83, v6
	v_mov_b32_e32 v84, v6
	v_mov_b32_e32 v85, v6
	v_mov_b32_e32 v102, v6
	v_mov_b32_e32 v103, v6
	v_mov_b32_e32 v104, v6
	v_mov_b32_e32 v105, v6
	v_mov_b32_e32 v98, v6
	v_mov_b32_e32 v99, v6
	v_mov_b32_e32 v100, v6
	v_mov_b32_e32 v101, v6
	v_mov_b32_e32 v122, v6
	v_mov_b32_e32 v123, v6
	v_mov_b32_e32 v124, v6
	v_mov_b32_e32 v125, v6
	v_mov_b32_e32 v114, v6
	v_mov_b32_e32 v115, v6
	v_mov_b32_e32 v116, v6
	v_mov_b32_e32 v117, v6
	v_mov_b32_e32 v78, v6
	v_mov_b32_e32 v79, v6
	v_mov_b32_e32 v80, v6
	v_mov_b32_e32 v81, v6
	v_mov_b32_e32 v74, v6
	v_mov_b32_e32 v75, v6
	v_mov_b32_e32 v76, v6
	v_mov_b32_e32 v77, v6
	v_mov_b32_e32 v94, v6
	v_mov_b32_e32 v95, v6
	v_mov_b32_e32 v96, v6
	v_mov_b32_e32 v97, v6
	v_mov_b32_e32 v90, v6
	v_mov_b32_e32 v91, v6
	v_mov_b32_e32 v92, v6
	v_mov_b32_e32 v93, v6
	v_mov_b32_e32 v110, v6
	v_mov_b32_e32 v111, v6
	v_mov_b32_e32 v112, v6
	v_mov_b32_e32 v113, v6
	v_mov_b32_e32 v106, v6
	v_mov_b32_e32 v107, v6
	v_mov_b32_e32 v108, v6
	v_mov_b32_e32 v109, v6
	v_mov_b32_e32 v126, v6
	v_mov_b32_e32 v127, v6
	v_mov_b32_e32 v128, v6
	v_mov_b32_e32 v129, v6
	v_mov_b32_e32 v118, v6
	v_mov_b32_e32 v119, v6
	v_mov_b32_e32 v120, v6
	v_mov_b32_e32 v121, v6
	.p2align 6

; template <class Epi, bool ALIGN_EPI>
; __device__ __forceinline__ void gemm_phase(LAS unsigned char* lds, const Gemm g, const StaticOrder& S, const Epi& E) {
;     ...
; #pragma unroll
;     for (int a = 0; a < 2; ++a)
; #pragma unroll
;         for (int b = 0; b < 2; ++b)
; #pragma unroll
;             for (int m = 0; m < 4; ++m)
; #pragma unroll
;                 for (int n = 0; n < 2; ++n) acc[a][b][m][n] = (f32x4){0.f, 0.f, 0.f, 0.f};
;     ...
;         const bool has_next = S.next(ui + 1, nxt);
;         const char* nA = has_next ? (const char*)g.A + (size_t)nxt.pb * g.sA * 2 + (size_t)nxt.pm * tsA : cA; const char* nB = has_next ? (const char*)g.Bt + (size_t)nxt.pb * g.sB * 2 + (size_t)nxt.pn * tsB : cB;
;         for (int t = 0; t < nt; t += 2) {
; __global__ void __launch_bounds__(NWAVES * 64, 2) mega_fwd(Args args) {
;     ...
;             { int one_ = 1, zero_ = 0, kq_ = 256; asm volatile("" : "+s"(one_), "+s"(zero_), "+s"(kq_)); pg8::Gemm gm{AUG + ((size_t)(g * 1024 + b * 512)) * 512, Wend + (size_t)g * 256 * 256, 512, 256, kq_, 512, 256, 0, 0, 1}; pg8::StaticOrder S; S.init(512, 256, 1, one_, zero_);
;               pg8::EpiE E{EB + ((size_t)(g * 1024 + b * 512)) * 256}; pg8::gemm_phase<pg8::EpiE, true>(lds, gm, S, E); }
.LBB0_668:
	s_ashr_i32 s19, s18, 31
	s_lshl_b64 s[22:23], s[18:19], 18
	s_add_u32 s22, s0, s22
	s_addc_u32 s23, s1, s23
	s_ashr_i32 s17, s16, 31
	s_lshl_b64 s[24:25], s[16:17], 17
	s_add_u32 s24, s34, s24
	v_mov_b32_e32 v129, 0
	s_addc_u32 s25, s35, s25
	s_and_b64 vcc, exec, s[2:3]
	v_mov_b32_e32 v128, v129
	v_mov_b32_e32 v127, v129
	v_mov_b32_e32 v126, v129
	v_mov_b32_e32 v125, v129
	v_mov_b32_e32 v124, v129
	v_mov_b32_e32 v123, v129
	v_mov_b32_e32 v122, v129
	v_mov_b32_e32 v113, v129
	v_mov_b32_e32 v112, v129
	v_mov_b32_e32 v111, v129
	v_mov_b32_e32 v110, v129
	v_mov_b32_e32 v109, v129
	v_mov_b32_e32 v108, v129
	v_mov_b32_e32 v107, v129
	v_mov_b32_e32 v106, v129
	v_mov_b32_e32 v97, v129
	v_mov_b32_e32 v96, v129
	v_mov_b32_e32 v95, v129
	v_mov_b32_e32 v94, v129
	v_mov_b32_e32 v93, v129
	v_mov_b32_e32 v92, v129
	v_mov_b32_e32 v91, v129
	v_mov_b32_e32 v90, v129
	v_mov_b32_e32 v81, v129
	v_mov_b32_e32 v80, v129
	v_mov_b32_e32 v79, v129
	v_mov_b32_e32 v78, v129
	v_mov_b32_e32 v77, v129
	v_mov_b32_e32 v76, v129
	v_mov_b32_e32 v75, v129
	v_mov_b32_e32 v74, v129
	v_mov_b32_e32 v121, v129
	v_mov_b32_e32 v120, v129
	v_mov_b32_e32 v119, v129
	v_mov_b32_e32 v118, v129
	v_mov_b32_e32 v117, v129
	v_mov_b32_e32 v116, v129
	v_mov_b32_e32 v115, v129
	v_mov_b32_e32 v114, v129
	v_mov_b32_e32 v105, v129
	v_mov_b32_e32 v104, v129
	v_mov_b32_e32 v103, v129
	v_mov_b32_e32 v102, v129
	v_mov_b32_e32 v101, v129
	v_mov_b32_e32 v100, v129
	v_mov_b32_e32 v99, v129
	v_mov_b32_e32 v98, v129
	v_mov_b32_e32 v89, v129
	v_mov_b32_e32 v88, v129
	v_mov_b32_e32 v87, v129
	v_mov_b32_e32 v86, v129
	v_mov_b32_e32 v85, v129
	v_mov_b32_e32 v84, v129
	v_mov_b32_e32 v83, v129
	v_mov_b32_e32 v82, v129
	v_mov_b32_e32 v73, v129
	v_mov_b32_e32 v72, v129
	v_mov_b32_e32 v71, v129
	v_mov_b32_e32 v70, v129
	v_mov_b32_e32 v69, v129
	v_mov_b32_e32 v68, v129
	v_mov_b32_e32 v67, v129
	v_mov_b32_e32 v66, v129
	v_mov_b32_e32 v65, v129
	v_mov_b32_e32 v64, v129
	v_mov_b32_e32 v63, v129
	v_mov_b32_e32 v62, v129
	v_mov_b32_e32 v61, v129
	v_mov_b32_e32 v60, v129
	v_mov_b32_e32 v59, v129
	v_mov_b32_e32 v58, v129
	v_mov_b32_e32 v49, v129
	v_mov_b32_e32 v48, v129
	v_mov_b32_e32 v47, v129
	v_mov_b32_e32 v46, v129
	v_mov_b32_e32 v45, v129
	v_mov_b32_e32 v44, v129
	v_mov_b32_e32 v43, v129
	v_mov_b32_e32 v42, v129
	v_mov_b32_e32 v33, v129
	v_mov_b32_e32 v32, v129
	v_mov_b32_e32 v31, v129
	v_mov_b32_e32 v30, v129
	v_mov_b32_e32 v29, v129
	v_mov_b32_e32 v28, v129
	v_mov_b32_e32 v27, v129
	v_mov_b32_e32 v26, v129
	v_mov_b32_e32 v17, v129
	v_mov_b32_e32 v16, v129
	v_mov_b32_e32 v15, v129
	v_mov_b32_e32 v14, v129
	v_mov_b32_e32 v13, v129
	v_mov_b32_e32 v12, v129
	v_mov_b32_e32 v11, v129
	v_mov_b32_e32 v10, v129
	v_mov_b32_e32 v57, v129
	v_mov_b32_e32 v56, v129
	v_mov_b32_e32 v55, v129
	v_mov_b32_e32 v54, v129
	v_mov_b32_e32 v53, v129
	v_mov_b32_e32 v52, v129
	v_mov_b32_e32 v51, v129
	v_mov_b32_e32 v50, v129
	v_mov_b32_e32 v41, v129
	v_mov_b32_e32 v40, v129
	v_mov_b32_e32 v39, v129
	v_mov_b32_e32 v38, v129
	v_mov_b32_e32 v37, v129
	v_mov_b32_e32 v36, v129
	v_mov_b32_e32 v35, v129
	v_mov_b32_e32 v34, v129
	v_mov_b32_e32 v25, v129
	v_mov_b32_e32 v24, v129
	v_mov_b32_e32 v23, v129
	v_mov_b32_e32 v22, v129
	v_mov_b32_e32 v21, v129
	v_mov_b32_e32 v20, v129
	v_mov_b32_e32 v19, v129
	v_mov_b32_e32 v18, v129
	v_mov_b32_e32 v9, v129
	v_mov_b32_e32 v8, v129
	v_mov_b32_e32 v7, v129
	v_mov_b32_e32 v6, v129
	v_mov_b32_e32 v5, v129
	v_mov_b32_e32 v4, v129
	v_mov_b32_e32 v3, v129
	v_mov_b32_e32 v2, v129
	s_cbranch_vccnz .LBB0_671
	s_and_b64 s[30:31], s[20:21], exec
	s_cselect_b32 s17, s23, s27
	s_cselect_b32 s19, s22, s26
	s_cselect_b32 s51, s25, s29
	s_cselect_b32 s52, s24, s28
	s_add_u32 s26, s26, 0x20080
	s_addc_u32 s27, s27, 0
	s_add_u32 s53, s28, 0x100
	v_mov_b32_e32 v2, 0
	s_addc_u32 s54, s29, 0
	s_mov_b32 s28, 0
	v_mov_b32_e32 v3, v2
	v_mov_b32_e32 v4, v2
	v_mov_b32_e32 v5, v2
	v_mov_b32_e32 v6, v2
	v_mov_b32_e32 v7, v2
	v_mov_b32_e32 v8, v2
	v_mov_b32_e32 v9, v2
	v_mov_b32_e32 v18, v2
	v_mov_b32_e32 v19, v2
	v_mov_b32_e32 v20, v2
	v_mov_b32_e32 v21, v2
	v_mov_b32_e32 v22, v2
	v_mov_b32_e32 v23, v2
	v_mov_b32_e32 v24, v2
	v_mov_b32_e32 v25, v2
	v_mov_b32_e32 v34, v2
	v_mov_b32_e32 v35, v2
	v_mov_b32_e32 v36, v2
	v_mov_b32_e32 v37, v2
	v_mov_b32_e32 v38, v2
	v_mov_b32_e32 v39, v2
	v_mov_b32_e32 v40, v2
	v_mov_b32_e32 v41, v2
	v_mov_b32_e32 v50, v2
	v_mov_b32_e32 v51, v2
	v_mov_b32_e32 v52, v2
	v_mov_b32_e32 v53, v2
	v_mov_b32_e32 v54, v2
	v_mov_b32_e32 v55, v2
	v_mov_b32_e32 v56, v2
	v_mov_b32_e32 v57, v2
	v_mov_b32_e32 v10, v2
	v_mov_b32_e32 v11, v2
	v_mov_b32_e32 v12, v2
	v_mov_b32_e32 v13, v2
	v_mov_b32_e32 v14, v2
	v_mov_b32_e32 v15, v2
	v_mov_b32_e32 v16, v2
	v_mov_b32_e32 v17, v2
	v_mov_b32_e32 v26, v2
	v_mov_b32_e32 v27, v2
	v_mov_b32_e32 v28, v2
	v_mov_b32_e32 v29, v2
	v_mov_b32_e32 v30, v2
	v_mov_b32_e32 v31, v2
	v_mov_b32_e32 v32, v2
	v_mov_b32_e32 v33, v2
	v_mov_b32_e32 v42, v2
	v_mov_b32_e32 v43, v2
	v_mov_b32_e32 v44, v2
	v_mov_b32_e32 v45, v2
	v_mov_b32_e32 v46, v2
	v_mov_b32_e32 v47, v2
	v_mov_b32_e32 v48, v2
	v_mov_b32_e32 v49, v2
	v_mov_b32_e32 v58, v2
	v_mov_b32_e32 v59, v2
	v_mov_b32_e32 v60, v2
	v_mov_b32_e32 v61, v2
	v_mov_b32_e32 v62, v2
	v_mov_b32_e32 v63, v2
	v_mov_b32_e32 v64, v2
	v_mov_b32_e32 v65, v2
	v_mov_b32_e32 v66, v2
	v_mov_b32_e32 v67, v2
	v_mov_b32_e32 v68, v2
	v_mov_b32_e32 v69, v2
	v_mov_b32_e32 v70, v2
	v_mov_b32_e32 v71, v2
	v_mov_b32_e32 v72, v2
	v_mov_b32_e32 v73, v2
	v_mov_b32_e32 v82, v2
	v_mov_b32_e32 v83, v2
	v_mov_b32_e32 v84, v2
	v_mov_b32_e32 v85, v2
	v_mov_b32_e32 v86, v2
	v_mov_b32_e32 v87, v2
	v_mov_b32_e32 v88, v2
	v_mov_b32_e32 v89, v2
	v_mov_b32_e32 v98, v2
	v_mov_b32_e32 v99, v2
	v_mov_b32_e32 v100, v2
	v_mov_b32_e32 v101, v2
	v_mov_b32_e32 v102, v2
	v_mov_b32_e32 v103, v2
	v_mov_b32_e32 v104, v2
	v_mov_b32_e32 v105, v2
	v_mov_b32_e32 v114, v2
	v_mov_b32_e32 v115, v2
	v_mov_b32_e32 v116, v2
	v_mov_b32_e32 v117, v2
	v_mov_b32_e32 v118, v2
	v_mov_b32_e32 v119, v2
	v_mov_b32_e32 v120, v2
	v_mov_b32_e32 v121, v2
	v_mov_b32_e32 v74, v2
	v_mov_b32_e32 v75, v2
	v_mov_b32_e32 v76, v2
	v_mov_b32_e32 v77, v2
	v_mov_b32_e32 v78, v2
	v_mov_b32_e32 v79, v2
	v_mov_b32_e32 v80, v2
	v_mov_b32_e32 v81, v2
	v_mov_b32_e32 v90, v2
	v_mov_b32_e32 v91, v2
	v_mov_b32_e32 v92, v2
	v_mov_b32_e32 v93, v2
	v_mov_b32_e32 v94, v2
	v_mov_b32_e32 v95, v2
	v_mov_b32_e32 v96, v2
	v_mov_b32_e32 v97, v2
	v_mov_b32_e32 v106, v2
	v_mov_b32_e32 v107, v2
	v_mov_b32_e32 v108, v2
	v_mov_b32_e32 v109, v2
	v_mov_b32_e32 v110, v2
	v_mov_b32_e32 v111, v2
	v_mov_b32_e32 v112, v2
	v_mov_b32_e32 v113, v2
	v_mov_b32_e32 v122, v2
	v_mov_b32_e32 v123, v2
	v_mov_b32_e32 v124, v2
	v_mov_b32_e32 v125, v2
	v_mov_b32_e32 v126, v2
	v_mov_b32_e32 v127, v2
	v_mov_b32_e32 v128, v2
	v_mov_b32_e32 v129, v2
	.p2align 6

; #define WAIT_BAR(N) asm volatile("s_waitcnt vmcnt(" #N ") lgkmcnt(0)\n\ts_barrier":::"memory")
;   #define DMA_K(t,slot) glds16(ksrc+(long)(t)*KVBLK*KP,(unsigned)__builtin_amdgcn_readfirstlane(kdst+(slot)))
;   #define DMA_V(t,slot) glds16(vsrc+(long)(t)*KVBLK*KP,(unsigned)__builtin_amdgcn_readfirstlane(vdst+(slot)))
;   #define START(P0,P1) do{ _Pragma("unroll") for(int r=0;r<16;++r)P0[r]=__builtin_amdgcn_exp2f(P0[r]); }while(0)
;   #define ROT() do{sl_prev=sl_cur;sl_cur=sl_next;sl_next=(sl_next==(NSLOT-1)*SLOTB)?0:sl_next+SLOTB;}while(0)
; template<int THRL> __device__ __forceinline__ void attn_unit(int b,int h,int qb,const bf16*Q,const bf16*__restrict__ K,const bf16*__restrict__ V,bf16*O,char*shm,float m2){
;     ...
;   const bf16*ksrc=Kh+(long)lane*KP+wid*8;
;   const bf16*vsrc=Vh+(long)(16*(wid&3)+(lane>>2))*KP+(wid>>2)*32+(lane&3)*8;
;   const unsigned kdst=lds0+LDS_K+wid*1024, vdst=lds0+LDS_V+wid*1024;
;     ...
;   const int vb0=(int)(lds0+LDS_V)+((lane>>4)&1)*32+(lane&3)*8+(4*hi+((lane&15)>>2))*64;
;   const char*Kbase=shm+LDS_K; bf16x8 kf[8];
;   const lds_cptr shm3=(lds_cptr)shm; const lds_cptr kp0=shm3+LDS_K+hi*1024+r32*16; const lds_cptr vp0=shm3+LDS_V+((lane>>4)&1)*32+(lane&3)*8+(4*hi+((lane&15)>>2))*64;
;   constexpr int NT=SEQ/KVBLK;
;   if(wid>=4)__builtin_amdgcn_s_setprio(1);
;   DMA_K(0,0);DMA_V(0,0);DMA_K(1,SLOTB);
;   bf16x8 qr[4];
;   #pragma unroll
;   for(int d0=0;d0<4;++d0)qr[d0]=*reinterpret_cast<const bf16x8*>(&Qw[(long)r32*QP+d0*16+hi*8]);
;   float l_reg=0.f;f32x16 o[2];o[0]=f32x16{};o[1]=f32x16{};f32x16 negm;
;   _Pragma("unroll") for(int r=0;r<16;++r)negm[r]=-m2;
;   asm volatile("":"+v"(negm));
;     ...
;   f32x16 pA0,pA1,pB0,pB1;
;   int sl_prev=0,sl_cur=0,sl_next=SLOTB;
;     ...
;   DMA_K(2,2*SLOTB);
;   WAIT_BAR(3);
;   qkt(pA0,pA1,Kbase,qr,negm,r32,hi);asm volatile("s_nop 15\n\ts_nop 7":"+v"(pA0),"+v"(pA1));
;   START(pA0,pA1);
;   _Pragma("unroll") for(int r=0;r<16;++r)pA1[r]=__builtin_amdgcn_exp2f(pA1[r]);
;   WAIT_BAR(0);
;   DMA_K(3,0);DMA_V(1,SLOTB);
;   ROT();
;   kload8(kf,kp0+sl_cur);
;   WAIT_BAR(2);
.LBB0_828:
	s_lshl_b32 s0, s0, 8
	s_lshr_b32 s9, s13, 6
	s_and_b32 s0, s0, 0x1f00
	s_or_b32 s0, s10, s0
	s_lshl_b32 s4, s9, 5
	s_add_u32 s4, s0, s4
	s_addc_u32 s5, s11, 0
	s_lshl_b64 s[4:5], s[4:5], 10
	s_add_u32 s54, s7, s4
	s_addc_u32 s55, s8, s5
	s_lshl_b32 s0, s9, 4
	s_lshr_b32 s18, s13, 2
	v_lshl_add_u64 v[212:213], v[192:193], 0, s[0:1]
	v_and_or_b32 v18, s18, 48, v218
	s_and_b32 s0, s18, 0x3fffffc0
	s_lshl_b32 s5, s9, 10
	v_lshlrev_b32_e32 v190, 8, v18
	s_cmp_lg_u32 0, -1
	v_lshl_add_u64 v[18:19], s[40:41], 0, v[190:191]
	s_cselect_b32 s4, 0, 0
	v_lshl_add_u64 v[18:19], v[18:19], 0, s[0:1]
	v_mov_b32_e32 v199, v191
	s_add_i32 s12, s5, s4
	s_mov_b32 s14, m0
	s_mov_b32 m0, s12
	s_nop 0
	global_load_lds_dwordx4 v[212:213], off
	s_mov_b32 m0, s14
	v_lshl_add_u64 v[210:211], v[18:19], 0, v[198:199]
	s_add_i32 s4, s12, 0x6000
	s_mov_b32 s14, m0
	s_mov_b32 m0, s4
	s_nop 0
	global_load_lds_dwordx4 v[210:211], off
	s_mov_b32 m0, s14
	v_lshl_add_u64 v[18:19], v[212:213], 0, s[42:43]
	s_add_i32 s14, s12, 0x2000
	s_mov_b32 s15, m0
	s_mov_b32 m0, s14
	s_nop 0
	global_load_lds_dwordx4 v[18:19], off
	s_mov_b32 m0, s15
	global_load_dwordx4 v[174:177], v229, s[54:55]
	global_load_dwordx4 v[170:173], v229, s[54:55] offset:32
	global_load_dwordx4 v[162:165], v229, s[54:55] offset:64
	global_load_dwordx4 v[154:157], v229, s[54:55] offset:96
	v_mov_b64_e32 v[64:65], v[16:17]
	v_mov_b64_e32 v[62:63], v[14:15]
	v_mov_b64_e32 v[60:61], v[12:13]
	v_mov_b64_e32 v[58:59], v[10:11]
	v_mov_b64_e32 v[56:57], v[8:9]
	v_mov_b64_e32 v[54:55], v[6:7]
	v_mov_b64_e32 v[52:53], v[4:5]
	v_mov_b64_e32 v[50:51], v[2:3]
	v_lshl_add_u64 v[18:19], v[212:213], 0, s[46:47]
	s_add_i32 s14, s12, 0x4000
	s_mov_b32 s15, m0
	s_mov_b32 m0, s14
	s_nop 0
	global_load_lds_dwordx4 v[18:19], off
	s_mov_b32 m0, s15
	s_waitcnt vmcnt(3) lgkmcnt(0)
	s_barrier
	ds_read_b128 v[18:21], v219
	ds_read_b128 v[22:25], v219 offset:512
	s_mov_b32 s19, s1
	s_and_b32 s18, s18, 0x3ffffff0
	s_lshl_b32 s20, s13, 6
	v_lshl_add_u64 v[214:215], v[194:195], 0, s[18:19]
	s_and_b32 s18, s20, 0x3000
	v_lshl_or_b32 v190, v228, 1, s18
	v_lshl_add_u64 v[48:49], v[212:213], 0, s[48:49]
	s_add_i32 s19, s12, 0x8000
	v_lshl_add_u64 v[98:99], v[210:211], 0, s[42:43]
	v_mov_b32_e32 v199, 0
	s_mov_b32 s14, -1
	s_mov_b32 s17, 0
	s_movk_i32 s16, 0x2000
	s_movk_i32 s15, 0x4000
	v_mov_b32_e32 v26, v199
	v_mov_b32_e32 v27, v199
	s_waitcnt vmcnt(3) lgkmcnt(1)
	v_mfma_f32_32x32x16_bf16 v[66:81], v[18:21], v[174:177], v[50:65]
	s_waitcnt lgkmcnt(0)
	v_mfma_f32_32x32x16_bf16 v[32:47], v[22:25], v[174:177], v[50:65]
	ds_read_b128 v[18:21], v219 offset:2048
	ds_read_b128 v[22:25], v219 offset:2560
	ds_read_b128 v[28:31], v219 offset:4608
	ds_read_b128 v[82:85], v219 offset:4096
	s_waitcnt vmcnt(2) lgkmcnt(3)
	v_mfma_f32_32x32x16_bf16 v[66:81], v[18:21], v[170:173], v[66:81]
	v_mov_b32_e32 v18, 0
	v_mov_b32_e32 v19, v199
	v_mov_b32_e32 v20, v199
	v_mov_b32_e32 v21, v199
	s_waitcnt lgkmcnt(2)
	v_mfma_f32_32x32x16_bf16 v[32:47], v[22:25], v[170:173], v[32:47]
	v_mov_b32_e32 v22, v199
	v_mov_b32_e32 v23, v199
	v_mov_b32_e32 v24, v199
	v_mov_b32_e32 v25, v199
	s_waitcnt vmcnt(1) lgkmcnt(0)
	v_mfma_f32_32x32x16_bf16 v[66:81], v[82:85], v[162:165], v[66:81]
	ds_read_b128 v[82:85], v219 offset:6656
	ds_read_b128 v[86:89], v219 offset:6144
	v_mfma_f32_32x32x16_bf16 v[32:47], v[28:31], v[162:165], v[32:47]
	v_mov_b32_e32 v28, v199
	v_mov_b32_e32 v29, v199
	v_mov_b32_e32 v30, v199
	v_mov_b32_e32 v31, v199
	s_waitcnt vmcnt(0) lgkmcnt(0)
	v_mfma_f32_32x32x16_bf16 v[66:81], v[86:89], v[154:157], v[66:81]
	v_lshl_add_u64 v[86:87], s[0:1], 0, v[190:191]
	v_lshl_add_u64 v[216:217], v[196:197], 0, v[86:87]
	v_mfma_f32_32x32x16_bf16 v[32:47], v[82:85], v[154:157], v[32:47]
	s_nop 15
	s_nop 7
	s_waitcnt vmcnt(0) lgkmcnt(0)
	s_barrier
	s_mov_b32 s0, m0
	s_mov_b32 m0, s12
	s_nop 0
	global_load_lds_dwordx4 v[48:49], off
	s_mov_b32 m0, s0
	v_mov_b32_e32 v48, v199
	s_mov_b32 s0, m0
	s_mov_b32 m0, s19
	s_nop 0
	global_load_lds_dwordx4 v[98:99], off
	s_mov_b32 m0, s0
	ds_read_b128 v[98:101], v219 offset:8192
	ds_read_b128 v[182:185], v219 offset:8704
	ds_read_b128 v[186:189], v219 offset:10240
	ds_read_b128 v[178:181], v219 offset:10752
	ds_read_b128 v[142:145], v219 offset:12288
	ds_read_b128 v[138:141], v219 offset:12800
	ds_read_b128 v[134:137], v219 offset:14336
	ds_read_b128 v[130:133], v219 offset:14848
	v_exp_f32_e32 v82, v66
	v_exp_f32_e32 v83, v67
	v_exp_f32_e32 v84, v68
	v_exp_f32_e32 v85, v69
	v_exp_f32_e32 v86, v70
	v_exp_f32_e32 v87, v71
	v_exp_f32_e32 v88, v72
	v_exp_f32_e32 v89, v73
	v_exp_f32_e32 v90, v74
	v_exp_f32_e32 v91, v75
	v_exp_f32_e32 v92, v76
	v_exp_f32_e32 v93, v77
	v_exp_f32_e32 v94, v78
	v_exp_f32_e32 v95, v79
	v_exp_f32_e32 v96, v80
	v_exp_f32_e32 v97, v81
	v_exp_f32_e32 v66, v32
	v_exp_f32_e32 v67, v33
	v_exp_f32_e32 v68, v34
	v_exp_f32_e32 v69, v35
	v_exp_f32_e32 v70, v36
	v_exp_f32_e32 v71, v37
	v_exp_f32_e32 v72, v38
	v_exp_f32_e32 v73, v39
	v_exp_f32_e32 v74, v40
	v_exp_f32_e32 v75, v41
	v_exp_f32_e32 v76, v42
	v_exp_f32_e32 v77, v43
	v_mov_b32_e32 v78, v44
	v_mov_b32_e32 v79, v45
	v_mov_b32_e32 v80, v46
	v_mov_b32_e32 v81, v47
	s_waitcnt vmcnt(2) lgkmcnt(0)
	s_barrier
	v_mov_b32_e32 v32, v199
	v_mov_b32_e32 v33, v199
	v_mov_b32_e32 v34, 0
	v_mov_b32_e32 v35, v199
	v_mov_b32_e32 v36, v199
	v_mov_b32_e32 v37, v199
	v_mov_b32_e32 v38, v199
	v_mov_b32_e32 v39, v199
	v_mov_b32_e32 v40, v199
	v_mov_b32_e32 v41, v199
	v_mov_b32_e32 v42, v199
	v_mov_b32_e32 v43, v199
	v_mov_b32_e32 v44, v199
	v_mov_b32_e32 v45, v199
	v_mov_b32_e32 v46, v199
	v_mov_b32_e32 v47, v199
	v_mov_b32_e32 v49, v199
	.p2align 6

; template <class Epi, bool ALIGN_EPI>
; __device__ __forceinline__ void gemm_phase(LAS unsigned char* lds, const Gemm g, const StaticOrder& S, const Epi& E) {
;     ...
; #pragma unroll
;     for (int a = 0; a < 2; ++a)
; #pragma unroll
;         for (int b = 0; b < 2; ++b)
; #pragma unroll
;             for (int m = 0; m < 4; ++m)
; #pragma unroll
;                 for (int n = 0; n < 2; ++n) acc[a][b][m][n] = (f32x4){0.f, 0.f, 0.f, 0.f};
;     ...
;         const bool has_next = S.next(ui + 1, nxt);
;         const char* nA = has_next ? (const char*)g.A + (size_t)nxt.pb * g.sA * 2 + (size_t)nxt.pm * tsA : cA; const char* nB = has_next ? (const char*)g.Bt + (size_t)nxt.pb * g.sB * 2 + (size_t)nxt.pn * tsB : cB;
;         for (int t = 0; t < nt; t += 2) {
; __global__ void __launch_bounds__(NWAVES * 64, 2) mega_fwd(Args args) {
;     ...
;             pg8::Gemm g{AUG, Wbig, 1024, 256, 512, 512, 512, (size_t)1024 * 512, (size_t)256 * 512, 32}; pg8::StaticOrder S; S.init(1024, 256, 32, G - 128, bx - 128);
;             pg8::EpiY E{ZB}; pg8::gemm_phase<pg8::EpiY, true>(lds, g, S, E); }
.LBB0_947:
	s_add_u32 s24, s24, 0x20080
	s_addc_u32 s25, s25, 0
	s_add_u32 s17, s26, 0x100
	v_mov_b32_e32 v2, 0
	s_addc_u32 s19, s27, 0
	s_mov_b32 s21, -2
	v_mov_b32_e32 v3, v2
	v_mov_b32_e32 v4, v2
	v_mov_b32_e32 v5, v2
	v_mov_b32_e32 v6, v2
	v_mov_b32_e32 v7, v2
	v_mov_b32_e32 v8, v2
	v_mov_b32_e32 v9, v2
	v_mov_b32_e32 v18, v2
	v_mov_b32_e32 v19, v2
	v_mov_b32_e32 v20, v2
	v_mov_b32_e32 v21, v2
	v_mov_b32_e32 v22, v2
	v_mov_b32_e32 v23, v2
	v_mov_b32_e32 v24, v2
	v_mov_b32_e32 v25, v2
	v_mov_b32_e32 v34, v2
	v_mov_b32_e32 v35, v2
	v_mov_b32_e32 v36, v2
	v_mov_b32_e32 v37, v2
	v_mov_b32_e32 v38, v2
	v_mov_b32_e32 v39, v2
	v_mov_b32_e32 v40, v2
	v_mov_b32_e32 v41, v2
	v_mov_b32_e32 v50, v2
	v_mov_b32_e32 v51, v2
	v_mov_b32_e32 v52, v2
	v_mov_b32_e32 v53, v2
	v_mov_b32_e32 v54, v2
	v_mov_b32_e32 v55, v2
	v_mov_b32_e32 v56, v2
	v_mov_b32_e32 v57, v2
	v_mov_b32_e32 v10, v2
	v_mov_b32_e32 v11, v2
	v_mov_b32_e32 v12, v2
	v_mov_b32_e32 v13, v2
	v_mov_b32_e32 v14, v2
	v_mov_b32_e32 v15, v2
	v_mov_b32_e32 v16, v2
	v_mov_b32_e32 v17, v2
	v_mov_b32_e32 v26, v2
	v_mov_b32_e32 v27, v2
	v_mov_b32_e32 v28, v2
	v_mov_b32_e32 v29, v2
	v_mov_b32_e32 v30, v2
	v_mov_b32_e32 v31, v2
	v_mov_b32_e32 v32, v2
	v_mov_b32_e32 v33, v2
	v_mov_b32_e32 v42, v2
	v_mov_b32_e32 v43, v2
	v_mov_b32_e32 v44, v2
	v_mov_b32_e32 v45, v2
	v_mov_b32_e32 v46, v2
	v_mov_b32_e32 v47, v2
	v_mov_b32_e32 v48, v2
	v_mov_b32_e32 v49, v2
	v_mov_b32_e32 v58, v2
	v_mov_b32_e32 v59, v2
	v_mov_b32_e32 v60, v2
	v_mov_b32_e32 v61, v2
	v_mov_b32_e32 v62, v2
	v_mov_b32_e32 v63, v2
	v_mov_b32_e32 v64, v2
	v_mov_b32_e32 v65, v2
	v_mov_b32_e32 v66, v2
	v_mov_b32_e32 v67, v2
	v_mov_b32_e32 v68, v2
	v_mov_b32_e32 v69, v2
	v_mov_b32_e32 v70, v2
	v_mov_b32_e32 v71, v2
	v_mov_b32_e32 v72, v2
	v_mov_b32_e32 v73, v2
	v_mov_b32_e32 v82, v2
	v_mov_b32_e32 v83, v2
	v_mov_b32_e32 v84, v2
	v_mov_b32_e32 v85, v2
	v_mov_b32_e32 v86, v2
	v_mov_b32_e32 v87, v2
	v_mov_b32_e32 v88, v2
	v_mov_b32_e32 v89, v2
	v_mov_b32_e32 v98, v2
	v_mov_b32_e32 v99, v2
	v_mov_b32_e32 v100, v2
	v_mov_b32_e32 v101, v2
	v_mov_b32_e32 v102, v2
	v_mov_b32_e32 v103, v2
	v_mov_b32_e32 v104, v2
	v_mov_b32_e32 v105, v2
	v_mov_b32_e32 v114, v2
	v_mov_b32_e32 v115, v2
	v_mov_b32_e32 v116, v2
	v_mov_b32_e32 v117, v2
	v_mov_b32_e32 v118, v2
	v_mov_b32_e32 v119, v2
	v_mov_b32_e32 v120, v2
	v_mov_b32_e32 v121, v2
	v_mov_b32_e32 v74, v2
	v_mov_b32_e32 v75, v2
	v_mov_b32_e32 v76, v2
	v_mov_b32_e32 v77, v2
	v_mov_b32_e32 v78, v2
	v_mov_b32_e32 v79, v2
	v_mov_b32_e32 v80, v2
	v_mov_b32_e32 v81, v2
	v_mov_b32_e32 v90, v2
	v_mov_b32_e32 v91, v2
	v_mov_b32_e32 v92, v2
	v_mov_b32_e32 v93, v2
	v_mov_b32_e32 v94, v2
	v_mov_b32_e32 v95, v2
	v_mov_b32_e32 v96, v2
	v_mov_b32_e32 v97, v2
	v_mov_b32_e32 v106, v2
	v_mov_b32_e32 v107, v2
	v_mov_b32_e32 v108, v2
	v_mov_b32_e32 v109, v2
	v_mov_b32_e32 v110, v2
	v_mov_b32_e32 v111, v2
	v_mov_b32_e32 v112, v2
	v_mov_b32_e32 v113, v2
	v_mov_b32_e32 v122, v2
	v_mov_b32_e32 v123, v2
	v_mov_b32_e32 v124, v2
	v_mov_b32_e32 v125, v2
	v_mov_b32_e32 v126, v2
	v_mov_b32_e32 v127, v2
	v_mov_b32_e32 v128, v2
	v_mov_b32_e32 v129, v2
	.p2align 6

; template <class Epi, bool ALIGN_EPI>
; __device__ __forceinline__ void gemm_phase(LAS unsigned char* lds, const Gemm g, const StaticOrder& S, const Epi& E) {
;     ...
; #pragma unroll
;     for (int a = 0; a < 2; ++a)
; #pragma unroll
;         for (int b = 0; b < 2; ++b)
; #pragma unroll
;             for (int m = 0; m < 4; ++m)
; #pragma unroll
;                 for (int n = 0; n < 2; ++n) acc[a][b][m][n] = (f32x4){0.f, 0.f, 0.f, 0.f};
;     ...
;         const bool has_next = S.next(ui + 1, nxt);
;         const char* nA = has_next ? (const char*)g.A + (size_t)nxt.pb * g.sA * 2 + (size_t)nxt.pm * tsA : cA; const char* nB = has_next ? (const char*)g.Bt + (size_t)nxt.pb * g.sB * 2 + (size_t)nxt.pn * tsB : cB;
;         for (int t = 0; t < nt; t += 2) {
.LBB0_1026:
	s_ashr_i32 s9, s8, 31
	s_lshl_b64 s[22:23], s[8:9], 18
	s_add_u32 s22, s64, s22
	s_addc_u32 s23, s65, s23
	s_and_b64 s[28:29], s[2:3], exec
	s_cselect_b32 s9, s23, s27
	s_cselect_b32 s47, s22, s26
	s_ashr_i32 s21, s20, 31
	s_lshl_b64 s[28:29], s[20:21], 18
	s_add_u32 s28, s82, s28
	s_addc_u32 s29, s83, s29
	s_and_b64 s[34:35], s[2:3], exec
	s_cselect_b32 s21, s29, s31
	s_cselect_b32 s48, s28, s30
	s_add_u32 s26, s26, 0x20080
	s_addc_u32 s27, s27, 0
	s_add_u32 s49, s30, 0x100
	v_mov_b32_e32 v2, 0
	s_addc_u32 s50, s31, 0
	s_mov_b32 s51, -2
	v_mov_b32_e32 v3, v2
	v_mov_b32_e32 v4, v2
	v_mov_b32_e32 v5, v2
	v_mov_b32_e32 v6, v2
	v_mov_b32_e32 v7, v2
	v_mov_b32_e32 v8, v2
	v_mov_b32_e32 v9, v2
	v_mov_b32_e32 v18, v2
	v_mov_b32_e32 v19, v2
	v_mov_b32_e32 v20, v2
	v_mov_b32_e32 v21, v2
	v_mov_b32_e32 v22, v2
	v_mov_b32_e32 v23, v2
	v_mov_b32_e32 v24, v2
	v_mov_b32_e32 v25, v2
	v_mov_b32_e32 v34, v2
	v_mov_b32_e32 v35, v2
	v_mov_b32_e32 v36, v2
	v_mov_b32_e32 v37, v2
	v_mov_b32_e32 v38, v2
	v_mov_b32_e32 v39, v2
	v_mov_b32_e32 v40, v2
	v_mov_b32_e32 v41, v2
	v_mov_b32_e32 v50, v2
	v_mov_b32_e32 v51, v2
	v_mov_b32_e32 v52, v2
	v_mov_b32_e32 v53, v2
	v_mov_b32_e32 v54, v2
	v_mov_b32_e32 v55, v2
	v_mov_b32_e32 v56, v2
	v_mov_b32_e32 v57, v2
	v_mov_b32_e32 v10, v2
	v_mov_b32_e32 v11, v2
	v_mov_b32_e32 v12, v2
	v_mov_b32_e32 v13, v2
	v_mov_b32_e32 v14, v2
	v_mov_b32_e32 v15, v2
	v_mov_b32_e32 v16, v2
	v_mov_b32_e32 v17, v2
	v_mov_b32_e32 v26, v2
	v_mov_b32_e32 v27, v2
	v_mov_b32_e32 v28, v2
	v_mov_b32_e32 v29, v2
	v_mov_b32_e32 v30, v2
	v_mov_b32_e32 v31, v2
	v_mov_b32_e32 v32, v2
	v_mov_b32_e32 v33, v2
	v_mov_b32_e32 v42, v2
	v_mov_b32_e32 v43, v2
	v_mov_b32_e32 v44, v2
	v_mov_b32_e32 v45, v2
	v_mov_b32_e32 v46, v2
	v_mov_b32_e32 v47, v2
	v_mov_b32_e32 v48, v2
	v_mov_b32_e32 v49, v2
	v_mov_b32_e32 v58, v2
	v_mov_b32_e32 v59, v2
	v_mov_b32_e32 v60, v2
	v_mov_b32_e32 v61, v2
	v_mov_b32_e32 v62, v2
	v_mov_b32_e32 v63, v2
	v_mov_b32_e32 v64, v2
	v_mov_b32_e32 v65, v2
	v_mov_b32_e32 v66, v2
	v_mov_b32_e32 v67, v2
	v_mov_b32_e32 v68, v2
	v_mov_b32_e32 v69, v2
	v_mov_b32_e32 v70, v2
	v_mov_b32_e32 v71, v2
	v_mov_b32_e32 v72, v2
	v_mov_b32_e32 v73, v2
	v_mov_b32_e32 v94, v2
	v_mov_b32_e32 v95, v2
	v_mov_b32_e32 v96, v2
	v_mov_b32_e32 v97, v2
	v_mov_b32_e32 v102, v2
	v_mov_b32_e32 v103, v2
	v_mov_b32_e32 v104, v2
	v_mov_b32_e32 v105, v2
	v_mov_b32_e32 v122, v2
	v_mov_b32_e32 v123, v2
	v_mov_b32_e32 v124, v2
	v_mov_b32_e32 v125, v2
	v_mov_b32_e32 v126, v2
	v_mov_b32_e32 v127, v2
	v_mov_b32_e32 v128, v2
	v_mov_b32_e32 v129, v2
	v_mov_b32_e32 v146, v2
	v_mov_b32_e32 v147, v2
	v_mov_b32_e32 v148, v2
	v_mov_b32_e32 v149, v2
	v_mov_b32_e32 v150, v2
	v_mov_b32_e32 v151, v2
	v_mov_b32_e32 v152, v2
	v_mov_b32_e32 v153, v2
	v_mov_b32_e32 v78, v2
	v_mov_b32_e32 v79, v2
	v_mov_b32_e32 v80, v2
	v_mov_b32_e32 v81, v2
	v_mov_b32_e32 v86, v2
	v_mov_b32_e32 v87, v2
	v_mov_b32_e32 v88, v2
	v_mov_b32_e32 v89, v2
	v_mov_b32_e32 v110, v2
	v_mov_b32_e32 v111, v2
	v_mov_b32_e32 v112, v2
	v_mov_b32_e32 v113, v2
	v_mov_b32_e32 v118, v2
	v_mov_b32_e32 v119, v2
	v_mov_b32_e32 v120, v2
	v_mov_b32_e32 v121, v2
	v_mov_b32_e32 v134, v2
	v_mov_b32_e32 v135, v2
	v_mov_b32_e32 v136, v2
	v_mov_b32_e32 v137, v2
	v_mov_b32_e32 v142, v2
	v_mov_b32_e32 v143, v2
	v_mov_b32_e32 v144, v2
	v_mov_b32_e32 v145, v2
	v_mov_b32_e32 v158, v2
	v_mov_b32_e32 v159, v2
	v_mov_b32_e32 v160, v2
	v_mov_b32_e32 v161, v2
	v_mov_b32_e32 v162, v2
	v_mov_b32_e32 v163, v2
	v_mov_b32_e32 v164, v2
	v_mov_b32_e32 v165, v2
	.p2align 6

; template <class Epi, bool ALIGN_EPI>
; __device__ __forceinline__ void gemm_phase(LAS unsigned char* lds, const Gemm g, const StaticOrder& S, const Epi& E) {
;     ...
; #pragma unroll
;     for (int a = 0; a < 2; ++a)
; #pragma unroll
;         for (int b = 0; b < 2; ++b)
; #pragma unroll
;             for (int m = 0; m < 4; ++m)
; #pragma unroll
;                 for (int n = 0; n < 2; ++n) acc[a][b][m][n] = (f32x4){0.f, 0.f, 0.f, 0.f};
;     ...
;         const bool has_next = S.next(ui + 1, nxt);
;         const char* nA = has_next ? (const char*)g.A + (size_t)nxt.pb * g.sA * 2 + (size_t)nxt.pm * tsA : cA; const char* nB = has_next ? (const char*)g.Bt + (size_t)nxt.pb * g.sB * 2 + (size_t)nxt.pn * tsB : cB;
;         for (int t = 0; t < nt; t += 2) {
.LBB0_1105:
	s_ashr_i32 s23, s22, 31
	s_lshl_b64 s[26:27], s[22:23], 18
	s_add_u32 s26, s76, s26
	s_addc_u32 s27, s77, s27
	s_and_b64 s[28:29], s[2:3], exec
	s_cselect_b32 s23, s27, s35
	s_cselect_b32 s51, s26, s34
	s_ashr_i32 s25, s24, 31
	s_lshl_b64 s[28:29], s[24:25], 18
	s_add_u32 s28, s70, s28
	s_addc_u32 s29, s71, s29
	s_and_b64 s[38:39], s[2:3], exec
	s_cselect_b32 s25, s29, s37
	s_cselect_b32 s52, s28, s36
	s_add_u32 s34, s34, 0x20080
	s_addc_u32 s35, s35, 0
	s_add_u32 s53, s36, 0x100
	v_mov_b32_e32 v2, 0
	s_addc_u32 s54, s37, 0
	s_mov_b32 s55, -2
	v_mov_b32_e32 v3, v2
	v_mov_b32_e32 v4, v2
	v_mov_b32_e32 v5, v2
	v_mov_b32_e32 v6, v2
	v_mov_b32_e32 v7, v2
	v_mov_b32_e32 v8, v2
	v_mov_b32_e32 v9, v2
	v_mov_b32_e32 v18, v2
	v_mov_b32_e32 v19, v2
	v_mov_b32_e32 v20, v2
	v_mov_b32_e32 v21, v2
	v_mov_b32_e32 v22, v2
	v_mov_b32_e32 v23, v2
	v_mov_b32_e32 v24, v2
	v_mov_b32_e32 v25, v2
	v_mov_b32_e32 v34, v2
	v_mov_b32_e32 v35, v2
	v_mov_b32_e32 v36, v2
	v_mov_b32_e32 v37, v2
	v_mov_b32_e32 v38, v2
	v_mov_b32_e32 v39, v2
	v_mov_b32_e32 v40, v2
	v_mov_b32_e32 v41, v2
	v_mov_b32_e32 v50, v2
	v_mov_b32_e32 v51, v2
	v_mov_b32_e32 v52, v2
	v_mov_b32_e32 v53, v2
	v_mov_b32_e32 v54, v2
	v_mov_b32_e32 v55, v2
	v_mov_b32_e32 v56, v2
	v_mov_b32_e32 v57, v2
	v_mov_b32_e32 v10, v2
	v_mov_b32_e32 v11, v2
	v_mov_b32_e32 v12, v2
	v_mov_b32_e32 v13, v2
	v_mov_b32_e32 v14, v2
	v_mov_b32_e32 v15, v2
	v_mov_b32_e32 v16, v2
	v_mov_b32_e32 v17, v2
	v_mov_b32_e32 v26, v2
	v_mov_b32_e32 v27, v2
	v_mov_b32_e32 v28, v2
	v_mov_b32_e32 v29, v2
	v_mov_b32_e32 v30, v2
	v_mov_b32_e32 v31, v2
	v_mov_b32_e32 v32, v2
	v_mov_b32_e32 v33, v2
	v_mov_b32_e32 v42, v2
	v_mov_b32_e32 v43, v2
	v_mov_b32_e32 v44, v2
	v_mov_b32_e32 v45, v2
	v_mov_b32_e32 v46, v2
	v_mov_b32_e32 v47, v2
	v_mov_b32_e32 v48, v2
	v_mov_b32_e32 v49, v2
	v_mov_b32_e32 v58, v2
	v_mov_b32_e32 v59, v2
	v_mov_b32_e32 v60, v2
	v_mov_b32_e32 v61, v2
	v_mov_b32_e32 v62, v2
	v_mov_b32_e32 v63, v2
	v_mov_b32_e32 v64, v2
	v_mov_b32_e32 v65, v2
	v_mov_b32_e32 v66, v2
	v_mov_b32_e32 v67, v2
	v_mov_b32_e32 v68, v2
	v_mov_b32_e32 v69, v2
	v_mov_b32_e32 v70, v2
	v_mov_b32_e32 v71, v2
	v_mov_b32_e32 v72, v2
	v_mov_b32_e32 v73, v2
	v_mov_b32_e32 v82, v2
	v_mov_b32_e32 v83, v2
	v_mov_b32_e32 v84, v2
	v_mov_b32_e32 v85, v2
	v_mov_b32_e32 v86, v2
	v_mov_b32_e32 v87, v2
	v_mov_b32_e32 v88, v2
	v_mov_b32_e32 v89, v2
	v_mov_b32_e32 v98, v2
	v_mov_b32_e32 v99, v2
	v_mov_b32_e32 v100, v2
	v_mov_b32_e32 v101, v2
	v_mov_b32_e32 v102, v2
	v_mov_b32_e32 v103, v2
	v_mov_b32_e32 v104, v2
	v_mov_b32_e32 v105, v2
	v_mov_b32_e32 v110, v2
	v_mov_b32_e32 v111, v2
	v_mov_b32_e32 v112, v2
	v_mov_b32_e32 v113, v2
	v_mov_b32_e32 v114, v2
	v_mov_b32_e32 v115, v2
	v_mov_b32_e32 v116, v2
	v_mov_b32_e32 v117, v2
	v_mov_b32_e32 v74, v2
	v_mov_b32_e32 v75, v2
	v_mov_b32_e32 v76, v2
	v_mov_b32_e32 v77, v2
	v_mov_b32_e32 v78, v2
	v_mov_b32_e32 v79, v2
	v_mov_b32_e32 v80, v2
	v_mov_b32_e32 v81, v2
	v_mov_b32_e32 v90, v2
	v_mov_b32_e32 v91, v2
	v_mov_b32_e32 v92, v2
	v_mov_b32_e32 v93, v2
	v_mov_b32_e32 v94, v2
	v_mov_b32_e32 v95, v2
	v_mov_b32_e32 v96, v2
	v_mov_b32_e32 v97, v2
	v_mov_b32_e32 v106, v2
	v_mov_b32_e32 v107, v2
	v_mov_b32_e32 v108, v2
	v_mov_b32_e32 v109, v2
	v_mov_b32_e32 v118, v2
	v_mov_b32_e32 v119, v2
	v_mov_b32_e32 v120, v2
	v_mov_b32_e32 v121, v2
	v_mov_b32_e32 v122, v2
	v_mov_b32_e32 v123, v2
	v_mov_b32_e32 v124, v2
	v_mov_b32_e32 v125, v2
	v_mov_b32_e32 v126, v2
	v_mov_b32_e32 v127, v2
	v_mov_b32_e32 v128, v2
	v_mov_b32_e32 v129, v2
	s_waitcnt vmcnt(0)
	.p2align 6

; template <class Epi, bool ALIGN_EPI>
; __device__ __forceinline__ void gemm_phase(LAS unsigned char* lds, const Gemm g, const StaticOrder& S, const Epi& E) {
;     ...
; #pragma unroll
;     for (int a = 0; a < 2; ++a)
; #pragma unroll
;         for (int b = 0; b < 2; ++b)
; #pragma unroll
;             for (int m = 0; m < 4; ++m)
; #pragma unroll
;                 for (int n = 0; n < 2; ++n) acc[a][b][m][n] = (f32x4){0.f, 0.f, 0.f, 0.f};
;     ...
;         const bool has_next = S.next(ui + 1, nxt);
;         const char* nA = has_next ? (const char*)g.A + (size_t)nxt.pb * g.sA * 2 + (size_t)nxt.pm * tsA : cA; const char* nB = has_next ? (const char*)g.Bt + (size_t)nxt.pb * g.sB * 2 + (size_t)nxt.pn * tsB : cB;
;         for (int t = 0; t < nt; t += 2) {
.LBB0_1130:
	s_ashr_i32 s25, s24, 31
	s_lshl_b64 s[28:29], s[24:25], 18
	s_add_u32 s28, s0, s28
	s_addc_u32 s29, s1, s29
	s_and_b64 s[30:31], s[2:3], exec
	s_cselect_b32 s25, s29, s37
	s_cselect_b32 s53, s28, s36
	s_ashr_i32 s27, s26, 31
	s_lshl_b64 s[30:31], s[26:27], 18
	s_add_u32 s30, s62, s30
	s_addc_u32 s31, s63, s31
	s_and_b64 s[40:41], s[2:3], exec
	s_cselect_b32 s27, s31, s39
	s_cselect_b32 s54, s30, s38
	s_add_u32 s36, s36, 0x20080
	s_addc_u32 s37, s37, 0
	s_add_u32 s55, s38, 0x100
	v_mov_b32_e32 v2, 0
	s_addc_u32 s56, s39, 0
	s_mov_b32 s57, -2
	v_mov_b32_e32 v3, v2
	v_mov_b32_e32 v4, v2
	v_mov_b32_e32 v5, v2
	v_mov_b32_e32 v6, v2
	v_mov_b32_e32 v7, v2
	v_mov_b32_e32 v8, v2
	v_mov_b32_e32 v9, v2
	v_mov_b32_e32 v18, v2
	v_mov_b32_e32 v19, v2
	v_mov_b32_e32 v20, v2
	v_mov_b32_e32 v21, v2
	v_mov_b32_e32 v22, v2
	v_mov_b32_e32 v23, v2
	v_mov_b32_e32 v24, v2
	v_mov_b32_e32 v25, v2
	v_mov_b32_e32 v34, v2
	v_mov_b32_e32 v35, v2
	v_mov_b32_e32 v36, v2
	v_mov_b32_e32 v37, v2
	v_mov_b32_e32 v38, v2
	v_mov_b32_e32 v39, v2
	v_mov_b32_e32 v40, v2
	v_mov_b32_e32 v41, v2
	v_mov_b32_e32 v50, v2
	v_mov_b32_e32 v51, v2
	v_mov_b32_e32 v52, v2
	v_mov_b32_e32 v53, v2
	v_mov_b32_e32 v54, v2
	v_mov_b32_e32 v55, v2
	v_mov_b32_e32 v56, v2
	v_mov_b32_e32 v57, v2
	v_mov_b32_e32 v10, v2
	v_mov_b32_e32 v11, v2
	v_mov_b32_e32 v12, v2
	v_mov_b32_e32 v13, v2
	v_mov_b32_e32 v14, v2
	v_mov_b32_e32 v15, v2
	v_mov_b32_e32 v16, v2
	v_mov_b32_e32 v17, v2
	v_mov_b32_e32 v26, v2
	v_mov_b32_e32 v27, v2
	v_mov_b32_e32 v28, v2
	v_mov_b32_e32 v29, v2
	v_mov_b32_e32 v30, v2
	v_mov_b32_e32 v31, v2
	v_mov_b32_e32 v32, v2
	v_mov_b32_e32 v33, v2
	v_mov_b32_e32 v42, v2
	v_mov_b32_e32 v43, v2
	v_mov_b32_e32 v44, v2
	v_mov_b32_e32 v45, v2
	v_mov_b32_e32 v46, v2
	v_mov_b32_e32 v47, v2
	v_mov_b32_e32 v48, v2
	v_mov_b32_e32 v49, v2
	v_mov_b32_e32 v58, v2
	v_mov_b32_e32 v59, v2
	v_mov_b32_e32 v60, v2
	v_mov_b32_e32 v61, v2
	v_mov_b32_e32 v62, v2
	v_mov_b32_e32 v63, v2
	v_mov_b32_e32 v64, v2
	v_mov_b32_e32 v65, v2
	v_mov_b32_e32 v66, v2
	v_mov_b32_e32 v67, v2
	v_mov_b32_e32 v68, v2
	v_mov_b32_e32 v69, v2
	v_mov_b32_e32 v70, v2
	v_mov_b32_e32 v71, v2
	v_mov_b32_e32 v72, v2
	v_mov_b32_e32 v73, v2
	v_mov_b32_e32 v82, v2
	v_mov_b32_e32 v83, v2
	v_mov_b32_e32 v84, v2
	v_mov_b32_e32 v85, v2
	v_mov_b32_e32 v86, v2
	v_mov_b32_e32 v87, v2
	v_mov_b32_e32 v88, v2
	v_mov_b32_e32 v89, v2
	v_mov_b32_e32 v98, v2
	v_mov_b32_e32 v99, v2
	v_mov_b32_e32 v100, v2
	v_mov_b32_e32 v101, v2
	v_mov_b32_e32 v102, v2
	v_mov_b32_e32 v103, v2
	v_mov_b32_e32 v104, v2
	v_mov_b32_e32 v105, v2
	v_mov_b32_e32 v114, v2
	v_mov_b32_e32 v115, v2
	v_mov_b32_e32 v116, v2
	v_mov_b32_e32 v117, v2
	v_mov_b32_e32 v118, v2
	v_mov_b32_e32 v119, v2
	v_mov_b32_e32 v120, v2
	v_mov_b32_e32 v121, v2
	v_mov_b32_e32 v74, v2
	v_mov_b32_e32 v75, v2
	v_mov_b32_e32 v76, v2
	v_mov_b32_e32 v77, v2
	v_mov_b32_e32 v78, v2
	v_mov_b32_e32 v79, v2
	v_mov_b32_e32 v80, v2
	v_mov_b32_e32 v81, v2
	v_mov_b32_e32 v90, v2
	v_mov_b32_e32 v91, v2
	v_mov_b32_e32 v92, v2
	v_mov_b32_e32 v93, v2
	v_mov_b32_e32 v94, v2
	v_mov_b32_e32 v95, v2
	v_mov_b32_e32 v96, v2
	v_mov_b32_e32 v97, v2
	v_mov_b32_e32 v106, v2
	v_mov_b32_e32 v107, v2
	v_mov_b32_e32 v108, v2
	v_mov_b32_e32 v109, v2
	v_mov_b32_e32 v110, v2
	v_mov_b32_e32 v111, v2
	v_mov_b32_e32 v112, v2
	v_mov_b32_e32 v113, v2
	v_mov_b32_e32 v122, v2
	v_mov_b32_e32 v123, v2
	v_mov_b32_e32 v124, v2
	v_mov_b32_e32 v125, v2
	v_mov_b32_e32 v126, v2
	v_mov_b32_e32 v127, v2
	v_mov_b32_e32 v128, v2
	v_mov_b32_e32 v129, v2
	s_waitcnt vmcnt(0)
	.p2align 6

; template <class Epi, bool ALIGN_EPI>
; __device__ __forceinline__ void gemm_phase(LAS unsigned char* lds, const Gemm g, const StaticOrder& S, const Epi& E) {
;     ...
; #pragma unroll
;     for (int a = 0; a < 2; ++a)
; #pragma unroll
;         for (int b = 0; b < 2; ++b)
; #pragma unroll
;             for (int m = 0; m < 4; ++m)
; #pragma unroll
;                 for (int n = 0; n < 2; ++n) acc[a][b][m][n] = (f32x4){0.f, 0.f, 0.f, 0.f};
;     ...
;         const bool has_next = S.next(ui + 1, nxt);
;         const char* nA = has_next ? (const char*)g.A + (size_t)nxt.pb * g.sA * 2 + (size_t)nxt.pm * tsA : cA; const char* nB = has_next ? (const char*)g.Bt + (size_t)nxt.pb * g.sB * 2 + (size_t)nxt.pn * tsB : cB;
;         for (int t = 0; t < nt; t += 2) {
.LBB0_1211:
	s_ashr_i32 s13, s12, 31
	s_lshl_b64 s[16:17], s[12:13], 19
	s_add_u32 s16, s78, s16
	s_addc_u32 s17, s79, s17
	s_and_b64 s[18:19], s[4:5], exec
	s_cselect_b32 s13, s17, s25
	s_cselect_b32 s21, s16, s24
	s_ashr_i32 s15, s14, 31
	s_lshl_b64 s[18:19], s[14:15], 19
	v_readlane_b32 s28, v252, 16
	v_readlane_b32 s29, v252, 17
	s_add_u32 s18, s28, s18
	s_addc_u32 s19, s29, s19
	s_and_b64 s[28:29], s[4:5], exec
	s_cselect_b32 s15, s19, s27
	s_cselect_b32 s43, s18, s26
	s_add_u32 s24, s24, 0x40080
	s_addc_u32 s25, s25, 0
	s_add_u32 s44, s26, 0x100
	v_mov_b32_e32 v2, 0
	s_addc_u32 s45, s27, 0
	s_mov_b32 s46, -2
	s_waitcnt lgkmcnt(0)
	v_mov_b32_e32 v3, v2
	v_mov_b32_e32 v4, v2
	v_mov_b32_e32 v5, v2
	v_mov_b32_e32 v6, v2
	v_mov_b32_e32 v7, v2
	v_mov_b32_e32 v8, v2
	v_mov_b32_e32 v9, v2
	v_mov_b32_e32 v18, v2
	v_mov_b32_e32 v19, v2
	v_mov_b32_e32 v20, v2
	v_mov_b32_e32 v21, v2
	v_mov_b32_e32 v22, v2
	v_mov_b32_e32 v23, v2
	v_mov_b32_e32 v24, v2
	v_mov_b32_e32 v25, v2
	v_mov_b32_e32 v34, v2
	v_mov_b32_e32 v35, v2
	v_mov_b32_e32 v36, v2
	v_mov_b32_e32 v37, v2
	v_mov_b32_e32 v38, v2
	v_mov_b32_e32 v39, v2
	v_mov_b32_e32 v40, v2
	v_mov_b32_e32 v41, v2
	v_mov_b32_e32 v50, v2
	v_mov_b32_e32 v51, v2
	v_mov_b32_e32 v52, v2
	v_mov_b32_e32 v53, v2
	v_mov_b32_e32 v54, v2
	v_mov_b32_e32 v55, v2
	v_mov_b32_e32 v56, v2
	v_mov_b32_e32 v57, v2
	v_mov_b32_e32 v10, v2
	v_mov_b32_e32 v11, v2
	v_mov_b32_e32 v12, v2
	v_mov_b32_e32 v13, v2
	v_mov_b32_e32 v14, v2
	v_mov_b32_e32 v15, v2
	v_mov_b32_e32 v16, v2
	v_mov_b32_e32 v17, v2
	v_mov_b32_e32 v26, v2
	v_mov_b32_e32 v27, v2
	v_mov_b32_e32 v28, v2
	v_mov_b32_e32 v29, v2
	v_mov_b32_e32 v30, v2
	v_mov_b32_e32 v31, v2
	v_mov_b32_e32 v32, v2
	v_mov_b32_e32 v33, v2
	v_mov_b32_e32 v42, v2
	v_mov_b32_e32 v43, v2
	v_mov_b32_e32 v44, v2
	v_mov_b32_e32 v45, v2
	v_mov_b32_e32 v46, v2
	v_mov_b32_e32 v47, v2
	v_mov_b32_e32 v48, v2
	v_mov_b32_e32 v49, v2
	v_mov_b32_e32 v58, v2
	v_mov_b32_e32 v59, v2
	v_mov_b32_e32 v60, v2
	v_mov_b32_e32 v61, v2
	v_mov_b32_e32 v62, v2
	v_mov_b32_e32 v63, v2
	v_mov_b32_e32 v64, v2
	v_mov_b32_e32 v65, v2
	v_mov_b32_e32 v66, v2
	v_mov_b32_e32 v67, v2
	v_mov_b32_e32 v68, v2
	v_mov_b32_e32 v69, v2
	v_mov_b32_e32 v70, v2
	v_mov_b32_e32 v71, v2
	v_mov_b32_e32 v72, v2
	v_mov_b32_e32 v73, v2
	v_mov_b32_e32 v82, v2
	v_mov_b32_e32 v83, v2
	v_mov_b32_e32 v84, v2
	v_mov_b32_e32 v85, v2
	v_mov_b32_e32 v86, v2
	v_mov_b32_e32 v87, v2
	v_mov_b32_e32 v88, v2
	v_mov_b32_e32 v89, v2
	v_mov_b32_e32 v98, v2
	v_mov_b32_e32 v99, v2
	v_mov_b32_e32 v100, v2
	v_mov_b32_e32 v101, v2
	v_mov_b32_e32 v102, v2
	v_mov_b32_e32 v103, v2
	v_mov_b32_e32 v104, v2
	v_mov_b32_e32 v105, v2
	v_mov_b32_e32 v114, v2
	v_mov_b32_e32 v115, v2
	v_mov_b32_e32 v116, v2
	v_mov_b32_e32 v117, v2
	v_mov_b32_e32 v118, v2
	v_mov_b32_e32 v119, v2
	v_mov_b32_e32 v120, v2
	v_mov_b32_e32 v121, v2
	v_mov_b32_e32 v74, v2
	v_mov_b32_e32 v75, v2
	v_mov_b32_e32 v76, v2
	v_mov_b32_e32 v77, v2
	v_mov_b32_e32 v78, v2
	v_mov_b32_e32 v79, v2
	v_mov_b32_e32 v80, v2
	v_mov_b32_e32 v81, v2
	v_mov_b32_e32 v90, v2
	v_mov_b32_e32 v91, v2
	v_mov_b32_e32 v92, v2
	v_mov_b32_e32 v93, v2
	v_mov_b32_e32 v94, v2
	v_mov_b32_e32 v95, v2
	v_mov_b32_e32 v96, v2
	v_mov_b32_e32 v97, v2
	v_mov_b32_e32 v106, v2
	v_mov_b32_e32 v107, v2
	v_mov_b32_e32 v108, v2
	v_mov_b32_e32 v109, v2
	v_mov_b32_e32 v110, v2
	v_mov_b32_e32 v111, v2
	v_mov_b32_e32 v112, v2
	v_mov_b32_e32 v113, v2
	v_mov_b32_e32 v122, v2
	v_mov_b32_e32 v123, v2
	v_mov_b32_e32 v124, v2
	v_mov_b32_e32 v125, v2
	v_mov_b32_e32 v126, v2
	v_mov_b32_e32 v127, v2
	v_mov_b32_e32 v128, v2
	v_mov_b32_e32 v129, v2
	s_waitcnt vmcnt(0)
	.p2align 6

; template <class Epi, bool ALIGN_EPI>
; __device__ __forceinline__ void gemm_phase(LAS unsigned char* lds, const Gemm g, const StaticOrder& S, const Epi& E) {
;     ...
; #pragma unroll
;     for (int a = 0; a < 2; ++a)
; #pragma unroll
;         for (int b = 0; b < 2; ++b)
; #pragma unroll
;             for (int m = 0; m < 4; ++m)
; #pragma unroll
;                 for (int n = 0; n < 2; ++n) acc[a][b][m][n] = (f32x4){0.f, 0.f, 0.f, 0.f};
;     ...
;         const bool has_next = S.next(ui + 1, nxt);
;         const char* nA = has_next ? (const char*)g.A + (size_t)nxt.pb * g.sA * 2 + (size_t)nxt.pm * tsA : cA; const char* nB = has_next ? (const char*)g.Bt + (size_t)nxt.pb * g.sB * 2 + (size_t)nxt.pn * tsB : cB;
;         for (int t = 0; t < nt; t += 2) {
.LBB0_1298:
	s_ashr_i32 s11, s10, 31
	s_lshl_b64 s[14:15], s[10:11], 19
	s_add_u32 s14, s72, s14
	s_addc_u32 s15, s73, s15
	s_and_b64 s[16:17], s[2:3], exec
	s_cselect_b32 s11, s15, s21
	s_cselect_b32 s44, s14, s20
	s_ashr_i32 s13, s12, 31
	s_lshl_b64 s[16:17], s[12:13], 19
	v_readlane_b32 s24, v252, 20
	v_readlane_b32 s25, v252, 21
	s_add_u32 s16, s24, s16
	s_addc_u32 s17, s25, s17
	s_and_b64 s[24:25], s[2:3], exec
	s_cselect_b32 s13, s17, s23
	s_cselect_b32 s45, s16, s22
	s_add_u32 s20, s20, 0x40080
	s_addc_u32 s21, s21, 0
	s_add_u32 s46, s22, 0x100
	v_mov_b32_e32 v2, 0
	s_addc_u32 s47, s23, 0
	s_mov_b32 s48, -2
	v_mov_b32_e32 v3, v2
	v_mov_b32_e32 v4, v2
	v_mov_b32_e32 v5, v2
	v_mov_b32_e32 v6, v2
	v_mov_b32_e32 v7, v2
	v_mov_b32_e32 v8, v2
	v_mov_b32_e32 v9, v2
	v_mov_b32_e32 v18, v2
	v_mov_b32_e32 v19, v2
	v_mov_b32_e32 v20, v2
	v_mov_b32_e32 v21, v2
	v_mov_b32_e32 v22, v2
	v_mov_b32_e32 v23, v2
	v_mov_b32_e32 v24, v2
	v_mov_b32_e32 v25, v2
	v_mov_b32_e32 v34, v2
	v_mov_b32_e32 v35, v2
	v_mov_b32_e32 v36, v2
	v_mov_b32_e32 v37, v2
	v_mov_b32_e32 v38, v2
	v_mov_b32_e32 v39, v2
	v_mov_b32_e32 v40, v2
	v_mov_b32_e32 v41, v2
	v_mov_b32_e32 v50, v2
	v_mov_b32_e32 v51, v2
	v_mov_b32_e32 v52, v2
	v_mov_b32_e32 v53, v2
	v_mov_b32_e32 v54, v2
	v_mov_b32_e32 v55, v2
	v_mov_b32_e32 v56, v2
	v_mov_b32_e32 v57, v2
	v_mov_b32_e32 v10, v2
	v_mov_b32_e32 v11, v2
	v_mov_b32_e32 v12, v2
	v_mov_b32_e32 v13, v2
	v_mov_b32_e32 v14, v2
	v_mov_b32_e32 v15, v2
	v_mov_b32_e32 v16, v2
	v_mov_b32_e32 v17, v2
	v_mov_b32_e32 v26, v2
	v_mov_b32_e32 v27, v2
	v_mov_b32_e32 v28, v2
	v_mov_b32_e32 v29, v2
	v_mov_b32_e32 v30, v2
	v_mov_b32_e32 v31, v2
	v_mov_b32_e32 v32, v2
	v_mov_b32_e32 v33, v2
	v_mov_b32_e32 v42, v2
	v_mov_b32_e32 v43, v2
	v_mov_b32_e32 v44, v2
	v_mov_b32_e32 v45, v2
	v_mov_b32_e32 v46, v2
	v_mov_b32_e32 v47, v2
	v_mov_b32_e32 v48, v2
	v_mov_b32_e32 v49, v2
	v_mov_b32_e32 v58, v2
	v_mov_b32_e32 v59, v2
	v_mov_b32_e32 v60, v2
	v_mov_b32_e32 v61, v2
	v_mov_b32_e32 v62, v2
	v_mov_b32_e32 v63, v2
	v_mov_b32_e32 v64, v2
	v_mov_b32_e32 v65, v2
	v_mov_b32_e32 v66, v2
	v_mov_b32_e32 v67, v2
	v_mov_b32_e32 v68, v2
	v_mov_b32_e32 v69, v2
	v_mov_b32_e32 v70, v2
	v_mov_b32_e32 v71, v2
	v_mov_b32_e32 v72, v2
	v_mov_b32_e32 v73, v2
	v_mov_b32_e32 v82, v2
	v_mov_b32_e32 v83, v2
	v_mov_b32_e32 v84, v2
	v_mov_b32_e32 v85, v2
	v_mov_b32_e32 v86, v2
	v_mov_b32_e32 v87, v2
	v_mov_b32_e32 v88, v2
	v_mov_b32_e32 v89, v2
	v_mov_b32_e32 v98, v2
	v_mov_b32_e32 v99, v2
	v_mov_b32_e32 v100, v2
	v_mov_b32_e32 v101, v2
	v_mov_b32_e32 v110, v2
	v_mov_b32_e32 v111, v2
	v_mov_b32_e32 v112, v2
	v_mov_b32_e32 v113, v2
	v_mov_b32_e32 v122, v2
	v_mov_b32_e32 v123, v2
	v_mov_b32_e32 v124, v2
	v_mov_b32_e32 v125, v2
	v_mov_b32_e32 v126, v2
	v_mov_b32_e32 v127, v2
	v_mov_b32_e32 v128, v2
	v_mov_b32_e32 v129, v2
	v_mov_b32_e32 v74, v2
	v_mov_b32_e32 v75, v2
	v_mov_b32_e32 v76, v2
	v_mov_b32_e32 v77, v2
	v_mov_b32_e32 v78, v2
	v_mov_b32_e32 v79, v2
	v_mov_b32_e32 v80, v2
	v_mov_b32_e32 v81, v2
	v_mov_b32_e32 v90, v2
	v_mov_b32_e32 v91, v2
	v_mov_b32_e32 v92, v2
	v_mov_b32_e32 v93, v2
	v_mov_b32_e32 v94, v2
	v_mov_b32_e32 v95, v2
	v_mov_b32_e32 v96, v2
	v_mov_b32_e32 v97, v2
	v_mov_b32_e32 v102, v2
	v_mov_b32_e32 v103, v2
	v_mov_b32_e32 v104, v2
	v_mov_b32_e32 v105, v2
	v_mov_b32_e32 v106, v2
	v_mov_b32_e32 v107, v2
	v_mov_b32_e32 v108, v2
	v_mov_b32_e32 v109, v2
	v_mov_b32_e32 v114, v2
	v_mov_b32_e32 v115, v2
	v_mov_b32_e32 v116, v2
	v_mov_b32_e32 v117, v2
	v_mov_b32_e32 v118, v2
	v_mov_b32_e32 v119, v2
	v_mov_b32_e32 v120, v2
	v_mov_b32_e32 v121, v2
	s_waitcnt vmcnt(0)
	.p2align 6

; template <class Epi, bool ALIGN_EPI>
; __device__ __forceinline__ void gemm_phase(LAS unsigned char* lds, const Gemm g, const StaticOrder& S, const Epi& E) {
;     ...
; #pragma unroll
;     for (int a = 0; a < 2; ++a)
; #pragma unroll
;         for (int b = 0; b < 2; ++b)
; #pragma unroll
;             for (int m = 0; m < 4; ++m)
; #pragma unroll
;                 for (int n = 0; n < 2; ++n) acc[a][b][m][n] = (f32x4){0.f, 0.f, 0.f, 0.f};
;     ...
;         const bool has_next = S.next(ui + 1, nxt);
;         const char* nA = has_next ? (const char*)g.A + (size_t)nxt.pb * g.sA * 2 + (size_t)nxt.pm * tsA : cA; const char* nB = has_next ? (const char*)g.Bt + (size_t)nxt.pb * g.sB * 2 + (size_t)nxt.pn * tsB : cB;
;         for (int t = 0; t < nt; t += 2) {
.LBB0_1404:
	s_add_u32 s16, s16, 0xc000
	s_addc_u32 s17, s17, 0
	s_add_u32 s42, s18, 0x100
	v_mov_b32_e32 v2, 0
	s_addc_u32 s43, s19, 0
	s_mov_b32 s44, -2
	s_waitcnt lgkmcnt(0)
	v_mov_b32_e32 v3, v2
	v_mov_b32_e32 v4, v2
	v_mov_b32_e32 v5, v2
	v_mov_b32_e32 v6, v2
	v_mov_b32_e32 v7, v2
	v_mov_b32_e32 v8, v2
	v_mov_b32_e32 v9, v2
	v_mov_b32_e32 v18, v2
	v_mov_b32_e32 v19, v2
	v_mov_b32_e32 v20, v2
	v_mov_b32_e32 v21, v2
	v_mov_b32_e32 v22, v2
	v_mov_b32_e32 v23, v2
	v_mov_b32_e32 v24, v2
	v_mov_b32_e32 v25, v2
	v_mov_b32_e32 v34, v2
	v_mov_b32_e32 v35, v2
	v_mov_b32_e32 v36, v2
	v_mov_b32_e32 v37, v2
	v_mov_b32_e32 v38, v2
	v_mov_b32_e32 v39, v2
	v_mov_b32_e32 v40, v2
	v_mov_b32_e32 v41, v2
	v_mov_b32_e32 v50, v2
	v_mov_b32_e32 v51, v2
	v_mov_b32_e32 v52, v2
	v_mov_b32_e32 v53, v2
	v_mov_b32_e32 v54, v2
	v_mov_b32_e32 v55, v2
	v_mov_b32_e32 v56, v2
	v_mov_b32_e32 v57, v2
	v_mov_b32_e32 v10, v2
	v_mov_b32_e32 v11, v2
	v_mov_b32_e32 v12, v2
	v_mov_b32_e32 v13, v2
	v_mov_b32_e32 v14, v2
	v_mov_b32_e32 v15, v2
	v_mov_b32_e32 v16, v2
	v_mov_b32_e32 v17, v2
	v_mov_b32_e32 v26, v2
	v_mov_b32_e32 v27, v2
	v_mov_b32_e32 v28, v2
	v_mov_b32_e32 v29, v2
	v_mov_b32_e32 v30, v2
	v_mov_b32_e32 v31, v2
	v_mov_b32_e32 v32, v2
	v_mov_b32_e32 v33, v2
	v_mov_b32_e32 v42, v2
	v_mov_b32_e32 v43, v2
	v_mov_b32_e32 v44, v2
	v_mov_b32_e32 v45, v2
	v_mov_b32_e32 v46, v2
	v_mov_b32_e32 v47, v2
	v_mov_b32_e32 v48, v2
	v_mov_b32_e32 v49, v2
	v_mov_b32_e32 v58, v2
	v_mov_b32_e32 v59, v2
	v_mov_b32_e32 v60, v2
	v_mov_b32_e32 v61, v2
	v_mov_b32_e32 v62, v2
	v_mov_b32_e32 v63, v2
	v_mov_b32_e32 v64, v2
	v_mov_b32_e32 v65, v2
	v_mov_b32_e32 v66, v2
	v_mov_b32_e32 v67, v2
	v_mov_b32_e32 v68, v2
	v_mov_b32_e32 v69, v2
	v_mov_b32_e32 v70, v2
	v_mov_b32_e32 v71, v2
	v_mov_b32_e32 v72, v2
	v_mov_b32_e32 v73, v2
	v_mov_b32_e32 v82, v2
	v_mov_b32_e32 v83, v2
	v_mov_b32_e32 v84, v2
	v_mov_b32_e32 v85, v2
	v_mov_b32_e32 v86, v2
	v_mov_b32_e32 v87, v2
	v_mov_b32_e32 v88, v2
	v_mov_b32_e32 v89, v2
	v_mov_b32_e32 v98, v2
	v_mov_b32_e32 v99, v2
	v_mov_b32_e32 v100, v2
	v_mov_b32_e32 v101, v2
	v_mov_b32_e32 v102, v2
	v_mov_b32_e32 v103, v2
	v_mov_b32_e32 v104, v2
	v_mov_b32_e32 v105, v2
	v_mov_b32_e32 v114, v2
	v_mov_b32_e32 v115, v2
	v_mov_b32_e32 v116, v2
	v_mov_b32_e32 v117, v2
	v_mov_b32_e32 v118, v2
	v_mov_b32_e32 v119, v2
	v_mov_b32_e32 v120, v2
	v_mov_b32_e32 v121, v2
	v_mov_b32_e32 v74, v2
	v_mov_b32_e32 v75, v2
	v_mov_b32_e32 v76, v2
	v_mov_b32_e32 v77, v2
	v_mov_b32_e32 v78, v2
	v_mov_b32_e32 v79, v2
	v_mov_b32_e32 v80, v2
	v_mov_b32_e32 v81, v2
	v_mov_b32_e32 v90, v2
	v_mov_b32_e32 v91, v2
	v_mov_b32_e32 v92, v2
	v_mov_b32_e32 v93, v2
	v_mov_b32_e32 v94, v2
	v_mov_b32_e32 v95, v2
	v_mov_b32_e32 v96, v2
	v_mov_b32_e32 v97, v2
	v_mov_b32_e32 v106, v2
	v_mov_b32_e32 v107, v2
	v_mov_b32_e32 v108, v2
	v_mov_b32_e32 v109, v2
	v_mov_b32_e32 v110, v2
	v_mov_b32_e32 v111, v2
	v_mov_b32_e32 v112, v2
	v_mov_b32_e32 v113, v2
	v_mov_b32_e32 v122, v2
	v_mov_b32_e32 v123, v2
	v_mov_b32_e32 v124, v2
	v_mov_b32_e32 v125, v2
	v_mov_b32_e32 v126, v2
	v_mov_b32_e32 v127, v2
	v_mov_b32_e32 v128, v2
	v_mov_b32_e32 v129, v2
	s_waitcnt vmcnt(0)
	.p2align 6

; template <class Epi, bool ALIGN_EPI>
; __device__ __forceinline__ void gemm_phase(LAS unsigned char* lds, const Gemm g, const StaticOrder& S, const Epi& E) {
;     ...
; #pragma unroll
;     for (int a = 0; a < 2; ++a)
; #pragma unroll
;         for (int b = 0; b < 2; ++b)
; #pragma unroll
;             for (int m = 0; m < 4; ++m)
; #pragma unroll
;                 for (int n = 0; n < 2; ++n) acc[a][b][m][n] = (f32x4){0.f, 0.f, 0.f, 0.f};
;     ...
;         const bool has_next = S.next(ui + 1, nxt);
;         const char* nA = has_next ? (const char*)g.A + (size_t)nxt.pb * g.sA * 2 + (size_t)nxt.pm * tsA : cA; const char* nB = has_next ? (const char*)g.Bt + (size_t)nxt.pb * g.sB * 2 + (size_t)nxt.pn * tsB : cB;
;         for (int t = 0; t < nt; t += 2) {
.LBB0_1500:
	s_ashr_i32 s19, s18, 31
	s_lshl_b64 s[22:23], s[18:19], 19
	s_add_u32 s22, s72, s22
	s_addc_u32 s23, s73, s23
	s_and_b64 s[26:27], s[0:1], exec
	s_cselect_b32 s19, s23, s25
	s_cselect_b32 s45, s22, s24
	s_ashr_i32 s21, s20, 31
	s_lshl_b64 s[26:27], s[20:21], 19
	s_add_u32 s26, s60, s26
	s_addc_u32 s27, s61, s27
	s_and_b64 s[30:31], s[0:1], exec
	s_cselect_b32 s21, s27, s29
	s_cselect_b32 s46, s26, s28
	s_add_u32 s24, s24, 0x40080
	s_addc_u32 s25, s25, 0
	s_add_u32 s47, s28, 0x100
	v_mov_b32_e32 v0, 0
	s_addc_u32 s48, s29, 0
	s_mov_b32 s49, -2
	v_mov_b32_e32 v1, v0
	v_mov_b32_e32 v2, v0
	v_mov_b32_e32 v3, v0
	v_mov_b32_e32 v4, v0
	v_mov_b32_e32 v5, v0
	v_mov_b32_e32 v6, v0
	v_mov_b32_e32 v7, v0
	v_mov_b32_e32 v16, v0
	v_mov_b32_e32 v17, v0
	v_mov_b32_e32 v18, v0
	v_mov_b32_e32 v19, v0
	v_mov_b32_e32 v20, v0
	v_mov_b32_e32 v21, v0
	v_mov_b32_e32 v22, v0
	v_mov_b32_e32 v23, v0
	v_mov_b32_e32 v32, v0
	v_mov_b32_e32 v33, v0
	v_mov_b32_e32 v34, v0
	v_mov_b32_e32 v35, v0
	v_mov_b32_e32 v36, v0
	v_mov_b32_e32 v37, v0
	v_mov_b32_e32 v38, v0
	v_mov_b32_e32 v39, v0
	v_mov_b32_e32 v48, v0
	v_mov_b32_e32 v49, v0
	v_mov_b32_e32 v50, v0
	v_mov_b32_e32 v51, v0
	v_mov_b32_e32 v52, v0
	v_mov_b32_e32 v53, v0
	v_mov_b32_e32 v54, v0
	v_mov_b32_e32 v55, v0
	v_mov_b32_e32 v8, v0
	v_mov_b32_e32 v9, v0
	v_mov_b32_e32 v10, v0
	v_mov_b32_e32 v11, v0
	v_mov_b32_e32 v12, v0
	v_mov_b32_e32 v13, v0
	v_mov_b32_e32 v14, v0
	v_mov_b32_e32 v15, v0
	v_mov_b32_e32 v24, v0
	v_mov_b32_e32 v25, v0
	v_mov_b32_e32 v26, v0
	v_mov_b32_e32 v27, v0
	v_mov_b32_e32 v28, v0
	v_mov_b32_e32 v29, v0
	v_mov_b32_e32 v30, v0
	v_mov_b32_e32 v31, v0
	v_mov_b32_e32 v40, v0
	v_mov_b32_e32 v41, v0
	v_mov_b32_e32 v42, v0
	v_mov_b32_e32 v43, v0
	v_mov_b32_e32 v44, v0
	v_mov_b32_e32 v45, v0
	v_mov_b32_e32 v46, v0
	v_mov_b32_e32 v47, v0
	v_mov_b32_e32 v56, v0
	v_mov_b32_e32 v57, v0
	v_mov_b32_e32 v58, v0
	v_mov_b32_e32 v59, v0
	v_mov_b32_e32 v60, v0
	v_mov_b32_e32 v61, v0
	v_mov_b32_e32 v62, v0
	v_mov_b32_e32 v63, v0
	v_mov_b32_e32 v64, v0
	v_mov_b32_e32 v65, v0
	v_mov_b32_e32 v66, v0
	v_mov_b32_e32 v67, v0
	v_mov_b32_e32 v68, v0
	v_mov_b32_e32 v69, v0
	v_mov_b32_e32 v70, v0
	v_mov_b32_e32 v71, v0
	v_mov_b32_e32 v80, v0
	v_mov_b32_e32 v81, v0
	v_mov_b32_e32 v82, v0
	v_mov_b32_e32 v83, v0
	v_mov_b32_e32 v84, v0
	v_mov_b32_e32 v85, v0
	v_mov_b32_e32 v86, v0
	v_mov_b32_e32 v87, v0
	v_mov_b32_e32 v96, v0
	v_mov_b32_e32 v97, v0
	v_mov_b32_e32 v98, v0
	v_mov_b32_e32 v99, v0
	v_mov_b32_e32 v100, v0
	v_mov_b32_e32 v101, v0
	v_mov_b32_e32 v102, v0
	v_mov_b32_e32 v103, v0
	v_mov_b32_e32 v112, v0
	v_mov_b32_e32 v113, v0
	v_mov_b32_e32 v114, v0
	v_mov_b32_e32 v115, v0
	v_mov_b32_e32 v116, v0
	v_mov_b32_e32 v117, v0
	v_mov_b32_e32 v118, v0
	v_mov_b32_e32 v119, v0
	v_mov_b32_e32 v72, v0
	v_mov_b32_e32 v73, v0
	v_mov_b32_e32 v74, v0
	v_mov_b32_e32 v75, v0
	v_mov_b32_e32 v76, v0
	v_mov_b32_e32 v77, v0
	v_mov_b32_e32 v78, v0
	v_mov_b32_e32 v79, v0
	v_mov_b32_e32 v88, v0
	v_mov_b32_e32 v89, v0
	v_mov_b32_e32 v90, v0
	v_mov_b32_e32 v91, v0
	v_mov_b32_e32 v92, v0
	v_mov_b32_e32 v93, v0
	v_mov_b32_e32 v94, v0
	v_mov_b32_e32 v95, v0
	v_mov_b32_e32 v104, v0
	v_mov_b32_e32 v105, v0
	v_mov_b32_e32 v106, v0
	v_mov_b32_e32 v107, v0
	v_mov_b32_e32 v108, v0
	v_mov_b32_e32 v109, v0
	v_mov_b32_e32 v110, v0
	v_mov_b32_e32 v111, v0
	v_mov_b32_e32 v120, v0
	v_mov_b32_e32 v121, v0
	v_mov_b32_e32 v122, v0
	v_mov_b32_e32 v123, v0
	v_mov_b32_e32 v124, v0
	v_mov_b32_e32 v125, v0
	v_mov_b32_e32 v126, v0
	v_mov_b32_e32 v127, v0
	.p2align 6
